# SSD chunk-state phase: conv history rows loaded together with the row loads when all lanes use raw rows (one wait instead of four per conv item)
# baseline (speedup 1.0000x reference)
;     float w[4][8], bias[8], h[3][8];
; #pragma unroll
;     for (int k = 0; k < 4; ++k) { const f32x4 a = *(const f32x4*)(F.b_conv_w + k * B_CD + ch), b = *(const f32x4*)(F.b_conv_w + k * B_CD + ch + 4);
;         w[k][0] = a.x; w[k][1] = a.y; w[k][2] = a.z; w[k][3] = a.w; w[k][4] = b.x; w[k][5] = b.y; w[k][6] = b.z; w[k][7] = b.w; }
;     { const f32x4 a = *(const f32x4*)(F.b_conv_b + ch), b = *(const f32x4*)(F.b_conv_b + ch + 4);
;       bias[0] = a.x; bias[1] = a.y; bias[2] = a.z; bias[3] = a.w; bias[4] = b.x; bias[5] = b.y; bias[6] = b.z; bias[7] = b.w; }
;     v4u rr[NT];
; #pragma unroll
;     for (int j = 0; j < NT; ++j) rr[j] = *(const v4u*)(XBC + (size_t)(row0 + j) * B_CD + ch);
; #pragma unroll
;     for (int k = 0; k < 3; ++k) {
;         if (hist_kind == 0) {
; #pragma unroll
;             for (int e = 0; e < 8; ++e) h[k][e] = 0.f;
;         } else if (hist_kind == 2) { const f32x4 a = *(const f32x4*)(hist + (size_t)k * B_CD + ch), b = *(const f32x4*)(hist + (size_t)k * B_CD + ch + 4);
;             h[k][0] = a.x; h[k][1] = a.y; h[k][2] = a.z; h[k][3] = a.w; h[k][4] = b.x; h[k][5] = b.y; h[k][6] = b.z; h[k][7] = b.w;
;         } else { const v4u r = *(const v4u*)(XBC + (size_t)(row0 - 3 + k) * B_CD + ch);
;             h[k][0] = bflo(r.x); h[k][1] = bfhi(r.x); h[k][2] = bflo(r.y); h[k][3] = bfhi(r.y); h[k][4] = bflo(r.z); h[k][5] = bfhi(r.z); h[k][6] = bflo(r.w); h[k][7] = bfhi(r.w); }
;     }
.LBB0_1120:
	s_or_saveexec_b64 s[0:1], s[0:1]
	v_cndmask_b32_e64 v2, 0, 1, s[2:3]
	v_cndmask_b32_e32 v137, 2, v2, vcc
	v_mov_b32_e32 v5, 0
	v_mov_b32_e32 v4, 0
	v_mov_b32_e32 v3, 0
	v_mov_b32_e32 v2, 0
	s_xor_b64 exec, exec, s[0:1]
	s_cbranch_execz .LBB0_1140
	v_lshlrev_b32_e32 v140, 3, v101
	v_lshl_or_b32 v22, s65, 9, v140
	v_readlane_b32 s4, v251, 2
	v_lshlrev_b32_e32 v98, 2, v22
	v_readlane_b32 s18, v251, 16
	v_readlane_b32 s19, v251, 17
	v_add_u32_e32 v141, s71, v139
	v_readlane_b32 s5, v251, 3
	v_lshl_add_u64 v[14:15], s[18:19], 0, v[98:99]
	v_add_co_u32_e32 v8, vcc, 0x6000, v14
	v_readlane_b32 s6, v251, 4
	s_nop 0
	v_addc_co_u32_e32 v9, vcc, 0, v15, vcc
	v_add_co_u32_e32 v12, vcc, 0xc000, v14
	v_readlane_b32 s7, v251, 5
	v_readlane_b32 s8, v251, 6
	v_readlane_b32 s9, v251, 7
	v_readlane_b32 s10, v251, 8
	v_readlane_b32 s11, v251, 9
	v_readlane_b32 s12, v251, 10
	v_readlane_b32 s13, v251, 11
	v_readlane_b32 s14, v251, 12
	v_readlane_b32 s15, v251, 13
	v_readlane_b32 s16, v251, 14
	v_readlane_b32 s17, v251, 15
	v_addc_co_u32_e32 v13, vcc, 0, v15, vcc
	v_lshlrev_b32_e32 v108, 1, v22
	v_mov_b32_e32 v109, v99
	global_load_dwordx4 v[2:5], v98, s[18:19] offset:16
	global_load_dwordx4 v[26:29], v98, s[18:19]
	v_lshl_add_u64 v[6:7], v[14:15], 0, s[30:31]
	v_lshl_add_u64 v[10:11], v[14:15], 0, s[34:35]
	v_lshl_add_u64 v[16:17], v[14:15], 0, s[76:77]
	v_add_co_u32_e32 v14, vcc, 0x12000, v14
	v_readlane_b32 s4, v251, 26
	v_lshl_add_u64 v[120:121], s[20:21], 0, v[108:109]
	v_or_b32_e32 v70, 1, v141
	v_addc_co_u32_e32 v15, vcc, 0, v15, vcc
	v_readlane_b32 s5, v251, 27
	v_mad_i64_i32 v[22:23], s[2:3], v141, s56, v[120:121]
	v_mad_i64_i32 v[24:25], s[2:3], v70, s56, v[120:121]
	v_or_b32_e32 v71, 2, v141
	v_or_b32_e32 v74, 3, v141
	global_load_dwordx4 v[30:33], v[8:9], off
	s_nop 0
	global_load_dwordx4 v[6:9], v[6:7], off offset:16
	s_nop 0
	global_load_dwordx4 v[34:37], v[12:13], off
	s_nop 0
	global_load_dwordx4 v[10:13], v[10:11], off offset:16
	s_nop 0
	global_load_dwordx4 v[38:41], v[14:15], off
	s_nop 0
	global_load_dwordx4 v[14:17], v[16:17], off offset:16
	s_nop 0
	global_load_dwordx4 v[18:21], v98, s[4:5] offset:16
	global_load_dwordx4 v[42:45], v98, s[4:5]
	global_load_dwordx4 v[82:85], v[22:23], off
	global_load_dwordx4 v[66:69], v[24:25], off
	v_mad_i64_i32 v[22:23], s[2:3], v71, s56, v[120:121]
	v_mad_i64_i32 v[24:25], s[2:3], v74, s56, v[120:121]
	v_or_b32_e32 v75, 4, v141
	v_or_b32_e32 v76, 5, v141
	global_load_dwordx4 v[62:65], v[22:23], off
	global_load_dwordx4 v[58:61], v[24:25], off
	v_mad_i64_i32 v[22:23], s[2:3], v75, s56, v[120:121]
	v_mad_i64_i32 v[24:25], s[2:3], v76, s56, v[120:121]
	v_or_b32_e32 v77, 6, v141
	v_or_b32_e32 v78, 7, v141
	global_load_dwordx4 v[54:57], v[22:23], off
	global_load_dwordx4 v[50:53], v[24:25], off
	v_mad_i64_i32 v[22:23], s[2:3], v77, s56, v[120:121]
	v_mad_i64_i32 v[24:25], s[2:3], v78, s56, v[120:121]
	global_load_dwordx4 v[46:49], v[22:23], off
	s_nop 0
	global_load_dwordx4 v[22:25], v[24:25], off
	v_cmp_gt_u32_e32 vcc, 64, v103
	v_lshl_add_u64 v[72:73], s[36:37], 0, v[98:99]
	v_readlane_b32 s6, v251, 28
	v_cndmask_b32_e32 v109, 1, v137, vcc
	v_cmp_lt_i32_e32 vcc, 1, v109
	v_readlane_b32 s7, v251, 29
	v_readlane_b32 s8, v251, 30
	v_readlane_b32 s9, v251, 31
	v_readlane_b32 s10, v251, 32
	v_readlane_b32 s11, v251, 33
	v_readlane_b32 s12, v251, 34
	v_readlane_b32 s13, v251, 35
	v_readlane_b32 s14, v251, 36
	v_readlane_b32 s15, v251, 37
	v_readlane_b32 s16, v251, 38
	v_readlane_b32 s17, v251, 39
	v_readlane_b32 s18, v251, 40
	v_readlane_b32 s19, v251, 41
	v_cmp_ne_u32_e32 vcc, 1, v109
	s_cbranch_vccnz .Lp7_slow_0
	v_add_u32_e32 v79, -3, v141
	v_mad_i64_i32 v[80:81], s[74:75], v79, s56, v[120:121]
	global_load_dwordx4 v[200:203], v[80:81], off
	v_mad_i64_i32 v[122:123], s[2:3], v141, s56, 0
	v_mad_i64_i32 v[118:119], s[2:3], v70, s56, 0
	v_mad_i64_i32 v[116:117], s[2:3], v71, s56, 0
	v_mad_i64_i32 v[114:115], s[2:3], v74, s56, 0
	v_mad_i64_i32 v[112:113], s[2:3], v75, s56, 0
	v_mad_i64_i32 v[110:111], s[2:3], v76, s56, 0
	v_mad_i64_i32 v[106:107], s[2:3], v77, s56, 0
	v_mad_i64_i32 v[104:105], s[2:3], v78, s56, 0
	v_add_u32_e32 v70, -2, v141
	v_mad_i64_i32 v[70:71], s[74:75], v70, s56, v[120:121]
	global_load_dwordx4 v[204:207], v[70:71], off
	v_add_u32_e32 v70, -1, v141
	v_mad_i64_i32 v[70:71], s[74:75], v70, s56, v[120:121]
	global_load_dwordx4 v[208:211], v[70:71], off
	s_waitcnt vmcnt(0)
	v_lshlrev_b32_e32 v94, 16, v200
	v_and_b32_e32 v95, 0xffff0000, v200
	v_lshlrev_b32_e32 v96, 16, v201
	v_and_b32_e32 v97, 0xffff0000, v201
	v_lshlrev_b32_e32 v90, 16, v202
	v_and_b32_e32 v91, 0xffff0000, v202
	v_lshlrev_b32_e32 v92, 16, v203
	v_and_b32_e32 v93, 0xffff0000, v203
	v_lshlrev_b32_e32 v86, 16, v204
	v_and_b32_e32 v87, 0xffff0000, v204
	v_lshlrev_b32_e32 v88, 16, v205
	v_and_b32_e32 v89, 0xffff0000, v205
	v_lshlrev_b32_e32 v78, 16, v206
	v_and_b32_e32 v79, 0xffff0000, v206
	v_lshlrev_b32_e32 v80, 16, v207
	v_and_b32_e32 v81, 0xffff0000, v207
	v_lshlrev_b32_e32 v74, 16, v208
	v_and_b32_e32 v75, 0xffff0000, v208
	v_lshlrev_b32_e32 v76, 16, v209
	v_and_b32_e32 v77, 0xffff0000, v209
	v_lshlrev_b32_e32 v70, 16, v210
	v_and_b32_e32 v71, 0xffff0000, v210
	v_lshlrev_b32_e32 v72, 16, v211
	v_and_b32_e32 v73, 0xffff0000, v211
	s_branch .Lp7_join_0
.Lp7_slow_0:
	v_cmp_lt_i32_e32 vcc, 1, v109
	s_and_saveexec_b64 s[2:3], vcc
	s_xor_b64 s[2:3], exec, s[2:3]
	s_cbranch_execz .LBB0_1123
	global_load_dwordx4 v[90:93], v[72:73], off offset:16
	global_load_dwordx4 v[94:97], v[72:73], off

; __device__ __forceinline__ float silu_f(float v) { return v * __builtin_amdgcn_rcpf(1.0f + __builtin_amdgcn_exp2f(-1.44269504f * v)); }
; #define LAS __attribute__((address_space(3)))
; __device__ __forceinline__ unsigned pk2(float lo, float hi) { const cvt_f2 v = {lo, hi}; const cvt_b2 r = __builtin_convertvector(v, cvt_b2); return __builtin_bit_cast(unsigned, r); }
; __device__ __forceinline__ float silu_f(float v) { return v * __builtin_amdgcn_rcpf(1.0f + __builtin_amdgcn_exp2f(-1.44269504f * v)); }
;     ...
; #pragma unroll
;     for (int j = 0; j < NT; ++j) { const v4u r = rr[j];
;         const float cur[8] = {bflo(r.x), bfhi(r.x), bflo(r.y), bfhi(r.y), bflo(r.z), bfhi(r.z), bflo(r.w), bfhi(r.w)}; float o[8];
; #pragma unroll
;         for (int e = 0; e < 8; ++e) { const float a = bias[e] + w[0][e] * h[0][e] + w[1][e] * h[1][e] + w[2][e] * h[2][e] + w[3][e] * cur[e]; o[e] = silu_f(a); h[0][e] = h[1][e]; h[1][e] = h[2][e]; h[2][e] = cur[e]; }
;         v4u pk; pk.x = pk2(o[0], o[1]); pk.y = pk2(o[2], o[3]); pk.z = pk2(o[4], o[5]); pk.w = pk2(o[6], o[7]);
;         __builtin_nontemporal_store(pk, (v4u*)(XC + (size_t)(row0 + j) * B_CD + ch));
;         if (TOLDS) { if (SCALE) { const float wg = wgt[j]; pk.x = pk2(o[0] * wg, o[1] * wg); pk.y = pk2(o[2] * wg, o[3] * wg); pk.z = pk2(o[4] * wg, o[5] * wg); pk.w = pk2(o[6] * wg, o[7] * wg); }
;             *(LAS v4u*)(ldst + j * lstride) = pk; }
;     }
.Lp7_join_0:
	s_waitcnt vmcnt(0)
	v_pk_fma_f32 v[94:95], v[26:27], v[94:95], v[42:43]
	v_lshlrev_b32_e32 v120, 16, v82
	v_pk_fma_f32 v[94:95], v[30:31], v[86:87], v[94:95]
	v_and_b32_e32 v121, 0xffff0000, v82
	v_pk_fma_f32 v[94:95], v[34:35], v[74:75], v[94:95]
	v_and_b32_e32 v98, 0x1c0, v140
	v_pk_fma_f32 v[94:95], v[38:39], v[120:121], v[94:95]
	v_pk_fma_f32 v[90:91], v[2:3], v[90:91], v[18:19]
	v_mul_f32_e32 v82, 0xbfb8aa3b, v94
	v_exp_f32_e32 v82, v82
	v_pk_fma_f32 v[90:91], v[6:7], v[78:79], v[90:91]
	v_lshlrev_b32_e32 v98, 2, v98
	v_pk_fma_f32 v[90:91], v[10:11], v[70:71], v[90:91]
	v_add_f32_e32 v82, 1.0, v82
	v_rcp_f32_e32 v140, v82
	v_mul_f32_e32 v82, 0xbfb8aa3b, v95
	v_exp_f32_e32 v82, v82
	v_lshlrev_b32_e32 v109, 2, v139
	v_add3_u32 v98, 0, v98, v109
	v_mov_b32_e32 v109, v99
	v_add_f32_e32 v82, 1.0, v82
	v_rcp_f32_e32 v141, v82
	v_lshlrev_b32_e32 v82, 16, v83
	v_and_b32_e32 v83, 0xffff0000, v83
	v_lshl_add_u64 v[108:109], s[22:23], 0, v[108:109]
	v_pk_mul_f32 v[140:141], v[94:95], v[140:141]
	v_pk_fma_f32 v[94:95], v[28:29], v[96:97], v[44:45]
	v_lshl_add_u64 v[122:123], v[108:109], 0, v[122:123]
	v_pk_fma_f32 v[94:95], v[32:33], v[88:89], v[94:95]
	v_pk_fma_f32 v[86:87], v[26:27], v[86:87], v[42:43]
	v_pk_fma_f32 v[94:95], v[36:37], v[76:77], v[94:95]
	v_pk_fma_f32 v[86:87], v[30:31], v[74:75], v[86:87]
	v_pk_fma_f32 v[94:95], v[40:41], v[82:83], v[94:95]
	v_pk_fma_f32 v[86:87], v[34:35], v[120:121], v[86:87]
	v_mul_f32_e32 v96, 0xbfb8aa3b, v94
	v_mul_f32_e32 v97, 0xbfb8aa3b, v95
	v_exp_f32_e32 v96, v96
	v_exp_f32_e32 v97, v97
	v_lshl_add_u64 v[118:119], v[108:109], 0, v[118:119]
	v_add_f32_e32 v96, 1.0, v96
	v_add_f32_e32 v97, 1.0, v97
	v_rcp_f32_e32 v96, v96
	v_rcp_f32_e32 v97, v97
	s_nop 0
	v_pk_mul_f32 v[96:97], v[94:95], v[96:97]
	v_lshlrev_b32_e32 v94, 16, v84
	v_and_b32_e32 v95, 0xffff0000, v84
	v_pk_fma_f32 v[90:91], v[14:15], v[94:95], v[90:91]
	s_nop 0
	v_mul_f32_e32 v84, 0xbfb8aa3b, v90
	v_exp_f32_e32 v84, v84
	s_nop 0
	v_add_f32_e32 v84, 1.0, v84
	v_rcp_f32_e32 v142, v84
	v_mul_f32_e32 v84, 0xbfb8aa3b, v91
	v_exp_f32_e32 v84, v84
	s_nop 0
	v_add_f32_e32 v84, 1.0, v84
	v_rcp_f32_e32 v143, v84
	v_lshlrev_b32_e32 v84, 16, v85
	v_and_b32_e32 v85, 0xffff0000, v85
	v_pk_mul_f32 v[142:143], v[90:91], v[142:143]
	v_pk_fma_f32 v[90:91], v[4:5], v[92:93], v[20:21]
	s_nop 0
	v_pk_fma_f32 v[90:91], v[8:9], v[80:81], v[90:91]
	s_nop 0
	v_pk_fma_f32 v[90:91], v[12:13], v[72:73], v[90:91]
	s_nop 0
	v_pk_fma_f32 v[90:91], v[16:17], v[84:85], v[90:91]
	s_nop 0
	v_mul_f32_e32 v92, 0xbfb8aa3b, v90
	v_mul_f32_e32 v93, 0xbfb8aa3b, v91
	v_exp_f32_e32 v92, v92
	v_exp_f32_e32 v93, v93
	v_add_f32_e32 v92, 1.0, v92
	v_add_f32_e32 v93, 1.0, v93
	v_rcp_f32_e32 v92, v92
	v_rcp_f32_e32 v93, v93
	s_nop 0
	v_pk_mul_f32 v[144:145], v[90:91], v[92:93]
	v_cvt_pk_bf16_f32 v90, v140, v141
	v_cvt_pk_bf16_f32 v91, v96, v97
	v_cvt_pk_bf16_f32 v92, v142, v143
	v_cvt_pk_bf16_f32 v93, v144, v145
	global_store_dwordx4 v[122:123], v[90:93], off nt
	ds_read_b32 v122, v98 offset:4096
	s_waitcnt lgkmcnt(0)
	v_pk_mul_f32 v[90:91], v[140:141], v[122:123] op_sel_hi:[1,0]
	v_pk_mul_f32 v[92:93], v[122:123], v[96:97] op_sel_hi:[0,1]
	v_cvt_pk_bf16_f32 v90, v90, v91
	v_cvt_pk_bf16_f32 v91, v92, v93
	v_pk_mul_f32 v[92:93], v[122:123], v[142:143] op_sel_hi:[0,1]
	v_pk_mul_f32 v[96:97], v[122:123], v[144:145] op_sel_hi:[0,1]
	v_cvt_pk_bf16_f32 v92, v92, v93
	v_cvt_pk_bf16_f32 v93, v96, v97
	ds_write_b128 v138, v[90:93] offset:43008
	v_lshlrev_b32_e32 v92, 16, v66
	v_and_b32_e32 v93, 0xffff0000, v66
	v_pk_fma_f32 v[86:87], v[38:39], v[92:93], v[86:87]
	s_nop 0
	v_mul_f32_e32 v66, 0xbfb8aa3b, v86
	v_exp_f32_e32 v66, v66
	s_nop 0
	v_add_f32_e32 v66, 1.0, v66
	v_rcp_f32_e32 v90, v66
	v_mul_f32_e32 v66, 0xbfb8aa3b, v87
	v_exp_f32_e32 v66, v66
	s_nop 0
	v_add_f32_e32 v66, 1.0, v66
	v_rcp_f32_e32 v91, v66
	s_nop 0
	v_pk_mul_f32 v[96:97], v[86:87], v[90:91]
	v_lshlrev_b32_e32 v90, 16, v67
	v_and_b32_e32 v91, 0xffff0000, v67
	v_pk_fma_f32 v[66:67], v[28:29], v[88:89], v[44:45]
	v_lshlrev_b32_e32 v88, 16, v68
	v_pk_fma_f32 v[66:67], v[32:33], v[76:77], v[66:67]
	v_and_b32_e32 v89, 0xffff0000, v68
	v_pk_fma_f32 v[66:67], v[36:37], v[82:83], v[66:67]
	s_nop 0
	v_pk_fma_f32 v[66:67], v[40:41], v[90:91], v[66:67]
	s_nop 0
	v_mul_f32_e32 v86, 0xbfb8aa3b, v66
	v_mul_f32_e32 v87, 0xbfb8aa3b, v67
	v_exp_f32_e32 v86, v86
	v_exp_f32_e32 v87, v87
	v_add_f32_e32 v86, 1.0, v86
	v_add_f32_e32 v87, 1.0, v87
	v_rcp_f32_e32 v86, v86
	v_rcp_f32_e32 v87, v87
	s_nop 0
	v_pk_mul_f32 v[122:123], v[66:67], v[86:87]
	v_pk_fma_f32 v[66:67], v[2:3], v[78:79], v[18:19]
	v_lshlrev_b32_e32 v86, 16, v69
	v_pk_fma_f32 v[66:67], v[6:7], v[70:71], v[66:67]
	v_and_b32_e32 v87, 0xffff0000, v69
	v_pk_fma_f32 v[66:67], v[10:11], v[94:95], v[66:67]
	s_nop 0
	v_pk_fma_f32 v[66:67], v[14:15], v[88:89], v[66:67]
	s_nop 0
	v_mul_f32_e32 v68, 0xbfb8aa3b, v66
	v_exp_f32_e32 v68, v68
	s_nop 0
	v_add_f32_e32 v68, 1.0, v68
	v_rcp_f32_e32 v78, v68
	v_mul_f32_e32 v68, 0xbfb8aa3b, v67
	v_exp_f32_e32 v68, v68
	s_nop 0
	v_add_f32_e32 v68, 1.0, v68
	v_rcp_f32_e32 v79, v68
	s_nop 0
	v_pk_mul_f32 v[78:79], v[66:67], v[78:79]
	v_pk_fma_f32 v[66:67], v[4:5], v[80:81], v[20:21]
	s_nop 0
	v_pk_fma_f32 v[66:67], v[8:9], v[72:73], v[66:67]
	s_nop 0
	v_pk_fma_f32 v[66:67], v[12:13], v[84:85], v[66:67]
	s_nop 0
	v_pk_fma_f32 v[66:67], v[16:17], v[86:87], v[66:67]
	s_nop 0
	v_mul_f32_e32 v68, 0xbfb8aa3b, v66
	v_mul_f32_e32 v69, 0xbfb8aa3b, v67
	v_exp_f32_e32 v68, v68
	v_exp_f32_e32 v69, v69
	v_add_f32_e32 v68, 1.0, v68
	v_add_f32_e32 v69, 1.0, v69
	v_rcp_f32_e32 v68, v68
	v_rcp_f32_e32 v69, v69
	s_nop 0
	v_pk_mul_f32 v[80:81], v[66:67], v[68:69]
	v_cvt_pk_bf16_f32 v66, v96, v97
	v_cvt_pk_bf16_f32 v67, v122, v123
	v_cvt_pk_bf16_f32 v68, v78, v79
	v_cvt_pk_bf16_f32 v69, v80, v81
	global_store_dwordx4 v[118:119], v[66:69], off nt
	ds_read_b32 v118, v98 offset:4100
	s_waitcnt lgkmcnt(0)
; __device__ __forceinline__ float silu_f(float v) { return v * __builtin_amdgcn_rcpf(1.0f + __builtin_amdgcn_exp2f(-1.44269504f * v)); }
; #define LAS __attribute__((address_space(3)))
; __device__ __forceinline__ unsigned pk2(float lo, float hi) { const cvt_f2 v = {lo, hi}; const cvt_b2 r = __builtin_convertvector(v, cvt_b2); return __builtin_bit_cast(unsigned, r); }
; __device__ __forceinline__ float silu_f(float v) { return v * __builtin_amdgcn_rcpf(1.0f + __builtin_amdgcn_exp2f(-1.44269504f * v)); }
;     ...
;     for (int j = 0; j < NT; ++j) { const v4u r = rr[j];
;         const float cur[8] = {bflo(r.x), bfhi(r.x), bflo(r.y), bfhi(r.y), bflo(r.z), bfhi(r.z), bflo(r.w), bfhi(r.w)}; float o[8];
; #pragma unroll
;         for (int e = 0; e < 8; ++e) { const float a = bias[e] + w[0][e] * h[0][e] + w[1][e] * h[1][e] + w[2][e] * h[2][e] + w[3][e] * cur[e]; o[e] = silu_f(a); h[0][e] = h[1][e]; h[1][e] = h[2][e]; h[2][e] = cur[e]; }
;         v4u pk; pk.x = pk2(o[0], o[1]); pk.y = pk2(o[2], o[3]); pk.z = pk2(o[4], o[5]); pk.w = pk2(o[6], o[7]);
;         __builtin_nontemporal_store(pk, (v4u*)(XC + (size_t)(row0 + j) * B_CD + ch));
;         if (TOLDS) { if (SCALE) { const float wg = wgt[j]; pk.x = pk2(o[0] * wg, o[1] * wg); pk.y = pk2(o[2] * wg, o[3] * wg); pk.z = pk2(o[4] * wg, o[5] * wg); pk.w = pk2(o[6] * wg, o[7] * wg); }
;             *(LAS v4u*)(ldst + j * lstride) = pk; }
	v_pk_mul_f32 v[66:67], v[96:97], v[118:119] op_sel_hi:[1,0]
	v_pk_mul_f32 v[68:69], v[122:123], v[118:119] op_sel_hi:[1,0]
	v_cvt_pk_bf16_f32 v66, v66, v67
	v_cvt_pk_bf16_f32 v67, v68, v69
	v_pk_mul_f32 v[68:69], v[118:119], v[78:79] op_sel_hi:[0,1]
	v_pk_mul_f32 v[78:79], v[118:119], v[80:81] op_sel_hi:[0,1]
	v_cvt_pk_bf16_f32 v68, v68, v69
	v_cvt_pk_bf16_f32 v69, v78, v79
	ds_write_b128 v138, v[66:69] offset:44048
	v_pk_fma_f32 v[66:67], v[26:27], v[74:75], v[42:43]
	v_lshlrev_b32_e32 v80, 16, v62
	v_pk_fma_f32 v[66:67], v[30:31], v[120:121], v[66:67]
	v_and_b32_e32 v81, 0xffff0000, v62
	v_pk_fma_f32 v[66:67], v[34:35], v[92:93], v[66:67]
	v_lshlrev_b32_e32 v78, 16, v63
	v_pk_fma_f32 v[66:67], v[38:39], v[80:81], v[66:67]
	v_and_b32_e32 v79, 0xffff0000, v63
	v_mul_f32_e32 v62, 0xbfb8aa3b, v66
	v_exp_f32_e32 v62, v62
	v_lshlrev_b32_e32 v74, 16, v65
	v_and_b32_e32 v75, 0xffff0000, v65
	v_lshl_add_u64 v[96:97], v[108:109], 0, v[116:117]
	v_add_f32_e32 v62, 1.0, v62
	v_rcp_f32_e32 v68, v62
	v_mul_f32_e32 v62, 0xbfb8aa3b, v67
	v_exp_f32_e32 v62, v62
	s_nop 0
	v_add_f32_e32 v62, 1.0, v62
	v_rcp_f32_e32 v69, v62
	v_pk_fma_f32 v[62:63], v[28:29], v[76:77], v[44:45]
	v_lshlrev_b32_e32 v76, 16, v64
	v_pk_fma_f32 v[62:63], v[32:33], v[82:83], v[62:63]
	v_pk_mul_f32 v[66:67], v[66:67], v[68:69]
	v_pk_fma_f32 v[62:63], v[36:37], v[90:91], v[62:63]
	v_and_b32_e32 v77, 0xffff0000, v64
	v_pk_fma_f32 v[62:63], v[40:41], v[78:79], v[62:63]
	s_nop 0
	v_mul_f32_e32 v68, 0xbfb8aa3b, v62
	v_mul_f32_e32 v69, 0xbfb8aa3b, v63
	v_exp_f32_e32 v68, v68
	v_exp_f32_e32 v69, v69
	v_add_f32_e32 v68, 1.0, v68
	v_add_f32_e32 v69, 1.0, v69
	v_rcp_f32_e32 v68, v68
	v_rcp_f32_e32 v69, v69
	s_nop 0
	v_pk_mul_f32 v[68:69], v[62:63], v[68:69]
	v_pk_fma_f32 v[62:63], v[2:3], v[70:71], v[18:19]
	s_nop 0
	v_pk_fma_f32 v[62:63], v[6:7], v[94:95], v[62:63]
	s_nop 0
	v_pk_fma_f32 v[62:63], v[10:11], v[88:89], v[62:63]
	s_nop 0
	v_pk_fma_f32 v[62:63], v[14:15], v[76:77], v[62:63]
	s_nop 0
	v_mul_f32_e32 v64, 0xbfb8aa3b, v62
	v_exp_f32_e32 v64, v64
	s_nop 0
	v_add_f32_e32 v64, 1.0, v64
	v_rcp_f32_e32 v70, v64
	v_mul_f32_e32 v64, 0xbfb8aa3b, v63
	v_exp_f32_e32 v64, v64
	s_nop 0
	v_add_f32_e32 v64, 1.0, v64
	v_rcp_f32_e32 v71, v64
	s_nop 0
	v_pk_mul_f32 v[70:71], v[62:63], v[70:71]
	v_pk_fma_f32 v[62:63], v[4:5], v[72:73], v[20:21]
	s_nop 0
	v_pk_fma_f32 v[62:63], v[8:9], v[84:85], v[62:63]
	s_nop 0
	v_pk_fma_f32 v[62:63], v[12:13], v[86:87], v[62:63]
	s_nop 0
	v_pk_fma_f32 v[62:63], v[16:17], v[74:75], v[62:63]
	s_nop 0
	v_mul_f32_e32 v64, 0xbfb8aa3b, v62
	v_mul_f32_e32 v65, 0xbfb8aa3b, v63
	v_exp_f32_e32 v64, v64
	v_exp_f32_e32 v65, v65
	v_add_f32_e32 v64, 1.0, v64
	v_add_f32_e32 v65, 1.0, v65
	v_rcp_f32_e32 v64, v64
	v_rcp_f32_e32 v65, v65
	s_nop 0
	v_pk_mul_f32 v[72:73], v[62:63], v[64:65]
	v_cvt_pk_bf16_f32 v62, v66, v67
	v_cvt_pk_bf16_f32 v63, v68, v69
	v_cvt_pk_bf16_f32 v64, v70, v71
	v_cvt_pk_bf16_f32 v65, v72, v73
	global_store_dwordx4 v[96:97], v[62:65], off nt
	ds_read_b32 v96, v98 offset:4104
	s_waitcnt lgkmcnt(0)
	v_pk_mul_f32 v[62:63], v[66:67], v[96:97] op_sel_hi:[1,0]
	v_pk_mul_f32 v[64:65], v[68:69], v[96:97] op_sel_hi:[1,0]
	v_cvt_pk_bf16_f32 v62, v62, v63
	v_cvt_pk_bf16_f32 v63, v64, v65
	v_pk_mul_f32 v[64:65], v[70:71], v[96:97] op_sel_hi:[1,0]
	v_pk_mul_f32 v[66:67], v[96:97], v[72:73] op_sel_hi:[0,1]
	v_cvt_pk_bf16_f32 v64, v64, v65
	v_cvt_pk_bf16_f32 v65, v66, v67
	ds_write_b128 v138, v[62:65] offset:45088
	v_pk_fma_f32 v[62:63], v[26:27], v[120:121], v[42:43]
	v_lshlrev_b32_e32 v70, 16, v58
	v_pk_fma_f32 v[62:63], v[30:31], v[92:93], v[62:63]
	v_and_b32_e32 v71, 0xffff0000, v58
	v_pk_fma_f32 v[62:63], v[34:35], v[80:81], v[62:63]
	v_lshlrev_b32_e32 v68, 16, v59
	v_pk_fma_f32 v[62:63], v[38:39], v[70:71], v[62:63]
	v_and_b32_e32 v69, 0xffff0000, v59
	v_mul_f32_e32 v58, 0xbfb8aa3b, v62
	v_exp_f32_e32 v58, v58
	v_lshlrev_b32_e32 v66, 16, v60
	v_and_b32_e32 v67, 0xffff0000, v60
	v_add_f32_e32 v58, 1.0, v58
	v_rcp_f32_e32 v64, v58
	v_mul_f32_e32 v58, 0xbfb8aa3b, v63
	v_exp_f32_e32 v58, v58
	s_nop 0
	v_add_f32_e32 v58, 1.0, v58
	v_rcp_f32_e32 v65, v58
	v_pk_fma_f32 v[58:59], v[28:29], v[82:83], v[44:45]
	v_pk_mul_f32 v[62:63], v[62:63], v[64:65]
	v_pk_fma_f32 v[58:59], v[32:33], v[90:91], v[58:59]
	s_nop 0
	v_pk_fma_f32 v[58:59], v[36:37], v[78:79], v[58:59]
	s_nop 0
	v_pk_fma_f32 v[58:59], v[40:41], v[68:69], v[58:59]
	s_nop 0
	v_mul_f32_e32 v64, 0xbfb8aa3b, v58
	v_mul_f32_e32 v65, 0xbfb8aa3b, v59
	v_exp_f32_e32 v64, v64
	v_exp_f32_e32 v65, v65
	v_add_f32_e32 v64, 1.0, v64
	v_add_f32_e32 v65, 1.0, v65
	v_rcp_f32_e32 v64, v64
	v_rcp_f32_e32 v65, v65
	s_nop 0
	v_pk_mul_f32 v[72:73], v[58:59], v[64:65]
	v_pk_fma_f32 v[58:59], v[2:3], v[94:95], v[18:19]
	v_lshl_add_u64 v[94:95], v[108:109], 0, v[114:115]
	v_pk_fma_f32 v[58:59], v[6:7], v[88:89], v[58:59]
	s_nop 0
	v_pk_fma_f32 v[58:59], v[10:11], v[76:77], v[58:59]
	s_nop 0
	v_pk_fma_f32 v[58:59], v[14:15], v[66:67], v[58:59]
	s_nop 0
	v_mul_f32_e32 v60, 0xbfb8aa3b, v58
	v_exp_f32_e32 v60, v60
	s_nop 0
	v_add_f32_e32 v60, 1.0, v60
	v_rcp_f32_e32 v64, v60
	v_mul_f32_e32 v60, 0xbfb8aa3b, v59
	v_exp_f32_e32 v60, v60
	s_nop 0
	v_add_f32_e32 v60, 1.0, v60
	v_rcp_f32_e32 v65, v60
	s_nop 0
	v_pk_mul_f32 v[82:83], v[58:59], v[64:65]
	v_pk_fma_f32 v[58:59], v[4:5], v[84:85], v[20:21]
	v_lshlrev_b32_e32 v64, 16, v61
	v_pk_fma_f32 v[58:59], v[8:9], v[86:87], v[58:59]
	v_and_b32_e32 v65, 0xffff0000, v61
	v_pk_fma_f32 v[58:59], v[12:13], v[74:75], v[58:59]
	s_nop 0
	v_pk_fma_f32 v[58:59], v[16:17], v[64:65], v[58:59]
	s_nop 0
	v_mul_f32_e32 v60, 0xbfb8aa3b, v58
	v_mul_f32_e32 v61, 0xbfb8aa3b, v59
	v_exp_f32_e32 v60, v60
	v_exp_f32_e32 v61, v61
	v_add_f32_e32 v60, 1.0, v60
	v_add_f32_e32 v61, 1.0, v61
	v_rcp_f32_e32 v60, v60
	v_rcp_f32_e32 v61, v61
	s_nop 0
	v_pk_mul_f32 v[84:85], v[58:59], v[60:61]
	v_cvt_pk_bf16_f32 v58, v62, v63
	v_cvt_pk_bf16_f32 v59, v72, v73
	v_cvt_pk_bf16_f32 v60, v82, v83
	v_cvt_pk_bf16_f32 v61, v84, v85
	global_store_dwordx4 v[94:95], v[58:61], off nt
	ds_read_b32 v94, v98 offset:4108
	s_waitcnt lgkmcnt(0)
; __device__ __forceinline__ float silu_f(float v) { return v * __builtin_amdgcn_rcpf(1.0f + __builtin_amdgcn_exp2f(-1.44269504f * v)); }
; #define LAS __attribute__((address_space(3)))
; __device__ __forceinline__ unsigned pk2(float lo, float hi) { const cvt_f2 v = {lo, hi}; const cvt_b2 r = __builtin_convertvector(v, cvt_b2); return __builtin_bit_cast(unsigned, r); }
; __device__ __forceinline__ float silu_f(float v) { return v * __builtin_amdgcn_rcpf(1.0f + __builtin_amdgcn_exp2f(-1.44269504f * v)); }
;     ...
;     for (int j = 0; j < NT; ++j) { const v4u r = rr[j];
;         const float cur[8] = {bflo(r.x), bfhi(r.x), bflo(r.y), bfhi(r.y), bflo(r.z), bfhi(r.z), bflo(r.w), bfhi(r.w)}; float o[8];
; #pragma unroll
;         for (int e = 0; e < 8; ++e) { const float a = bias[e] + w[0][e] * h[0][e] + w[1][e] * h[1][e] + w[2][e] * h[2][e] + w[3][e] * cur[e]; o[e] = silu_f(a); h[0][e] = h[1][e]; h[1][e] = h[2][e]; h[2][e] = cur[e]; }
;         v4u pk; pk.x = pk2(o[0], o[1]); pk.y = pk2(o[2], o[3]); pk.z = pk2(o[4], o[5]); pk.w = pk2(o[6], o[7]);
;         __builtin_nontemporal_store(pk, (v4u*)(XC + (size_t)(row0 + j) * B_CD + ch));
;         if (TOLDS) { if (SCALE) { const float wg = wgt[j]; pk.x = pk2(o[0] * wg, o[1] * wg); pk.y = pk2(o[2] * wg, o[3] * wg); pk.z = pk2(o[4] * wg, o[5] * wg); pk.w = pk2(o[6] * wg, o[7] * wg); }
;             *(LAS v4u*)(ldst + j * lstride) = pk; }
	v_pk_mul_f32 v[58:59], v[62:63], v[94:95] op_sel_hi:[1,0]
	v_pk_mul_f32 v[60:61], v[72:73], v[94:95] op_sel_hi:[1,0]
	v_cvt_pk_bf16_f32 v58, v58, v59
	v_cvt_pk_bf16_f32 v59, v60, v61
	v_pk_mul_f32 v[60:61], v[82:83], v[94:95] op_sel_hi:[1,0]
	v_pk_mul_f32 v[62:63], v[84:85], v[94:95] op_sel_hi:[1,0]
	v_cvt_pk_bf16_f32 v60, v60, v61
	v_cvt_pk_bf16_f32 v61, v62, v63
	ds_write_b128 v138, v[58:61] offset:46128
	v_pk_fma_f32 v[58:59], v[26:27], v[92:93], v[42:43]
	v_lshlrev_b32_e32 v62, 16, v54
	v_pk_fma_f32 v[58:59], v[30:31], v[80:81], v[58:59]
	v_and_b32_e32 v63, 0xffff0000, v54
	v_pk_fma_f32 v[58:59], v[34:35], v[70:71], v[58:59]
	s_nop 0
	v_pk_fma_f32 v[58:59], v[38:39], v[62:63], v[58:59]
	s_nop 0
	v_mul_f32_e32 v54, 0xbfb8aa3b, v58
	v_exp_f32_e32 v54, v54
	s_nop 0
	v_add_f32_e32 v54, 1.0, v54
	v_rcp_f32_e32 v60, v54
	v_mul_f32_e32 v54, 0xbfb8aa3b, v59
	v_exp_f32_e32 v54, v54
	s_nop 0
	v_add_f32_e32 v54, 1.0, v54
	v_rcp_f32_e32 v61, v54
	s_nop 0
	v_pk_mul_f32 v[72:73], v[58:59], v[60:61]
	v_lshlrev_b32_e32 v60, 16, v55
	v_and_b32_e32 v61, 0xffff0000, v55
	v_pk_fma_f32 v[54:55], v[28:29], v[90:91], v[44:45]
	s_nop 0
	v_pk_fma_f32 v[54:55], v[32:33], v[78:79], v[54:55]
	s_nop 0
	v_pk_fma_f32 v[54:55], v[36:37], v[68:69], v[54:55]
	s_nop 0
	v_pk_fma_f32 v[54:55], v[40:41], v[60:61], v[54:55]
	s_nop 0
	v_mul_f32_e32 v58, 0xbfb8aa3b, v54
	v_mul_f32_e32 v59, 0xbfb8aa3b, v55
	v_exp_f32_e32 v58, v58
	v_exp_f32_e32 v59, v59
	v_add_f32_e32 v58, 1.0, v58
	v_add_f32_e32 v59, 1.0, v59
	v_rcp_f32_e32 v58, v58
	v_rcp_f32_e32 v59, v59
	s_nop 0
	v_pk_mul_f32 v[90:91], v[54:55], v[58:59]
	v_pk_fma_f32 v[54:55], v[2:3], v[88:89], v[18:19]
	v_lshlrev_b32_e32 v58, 16, v56
	v_pk_fma_f32 v[54:55], v[6:7], v[76:77], v[54:55]
	v_and_b32_e32 v59, 0xffff0000, v56
	v_pk_fma_f32 v[54:55], v[10:11], v[66:67], v[54:55]
	s_nop 0
	v_pk_fma_f32 v[54:55], v[14:15], v[58:59], v[54:55]
	s_nop 0
	v_mul_f32_e32 v56, 0xbfb8aa3b, v54
	v_exp_f32_e32 v56, v56
	s_nop 0
	v_add_f32_e32 v56, 1.0, v56
	v_rcp_f32_e32 v82, v56
	v_mul_f32_e32 v56, 0xbfb8aa3b, v55
	v_exp_f32_e32 v56, v56
	s_nop 0
	v_add_f32_e32 v56, 1.0, v56
	v_rcp_f32_e32 v83, v56
	s_nop 0
	v_pk_mul_f32 v[88:89], v[54:55], v[82:83]
	v_lshlrev_b32_e32 v54, 16, v57
	v_and_b32_e32 v55, 0xffff0000, v57
	v_pk_fma_f32 v[56:57], v[4:5], v[86:87], v[20:21]
	v_cvt_pk_bf16_f32 v84, v88, v89
	v_pk_fma_f32 v[56:57], v[8:9], v[74:75], v[56:57]
	v_lshl_add_u64 v[86:87], v[108:109], 0, v[112:113]
	v_pk_fma_f32 v[56:57], v[12:13], v[64:65], v[56:57]
	s_nop 0
	v_pk_fma_f32 v[56:57], v[16:17], v[54:55], v[56:57]
	s_nop 0
	v_mul_f32_e32 v82, 0xbfb8aa3b, v56
	v_mul_f32_e32 v83, 0xbfb8aa3b, v57
	v_exp_f32_e32 v82, v82
	v_exp_f32_e32 v83, v83
	v_add_f32_e32 v82, 1.0, v82
	v_add_f32_e32 v83, 1.0, v83
	v_rcp_f32_e32 v82, v82
	v_rcp_f32_e32 v83, v83
	s_nop 0
	v_pk_mul_f32 v[56:57], v[56:57], v[82:83]
	v_cvt_pk_bf16_f32 v82, v72, v73
	v_cvt_pk_bf16_f32 v83, v90, v91
	v_cvt_pk_bf16_f32 v85, v56, v57
	global_store_dwordx4 v[86:87], v[82:85], off nt
	ds_read_b32 v86, v98 offset:4112
	s_waitcnt lgkmcnt(0)
	v_pk_mul_f32 v[72:73], v[72:73], v[86:87] op_sel_hi:[1,0]
	s_nop 0
	v_cvt_pk_bf16_f32 v82, v72, v73
	v_pk_mul_f32 v[72:73], v[90:91], v[86:87] op_sel_hi:[1,0]
	v_pk_mul_f32 v[56:57], v[56:57], v[86:87] op_sel_hi:[1,0]
	v_cvt_pk_bf16_f32 v83, v72, v73
	v_pk_mul_f32 v[72:73], v[88:89], v[86:87] op_sel_hi:[1,0]
	v_cvt_pk_bf16_f32 v85, v56, v57
	v_pk_fma_f32 v[56:57], v[26:27], v[80:81], v[42:43]
	v_cvt_pk_bf16_f32 v84, v72, v73
	v_pk_fma_f32 v[56:57], v[30:31], v[70:71], v[56:57]
	ds_write_b128 v138, v[82:85] offset:47168
	v_lshlrev_b32_e32 v82, 16, v50
	v_and_b32_e32 v83, 0xffff0000, v50
	v_pk_fma_f32 v[56:57], v[34:35], v[62:63], v[56:57]
	v_lshl_add_u64 v[86:87], v[108:109], 0, v[110:111]
	v_pk_fma_f32 v[56:57], v[38:39], v[82:83], v[56:57]
	s_nop 0
	v_mul_f32_e32 v50, 0xbfb8aa3b, v56
	v_exp_f32_e32 v50, v50
	s_nop 0
	v_add_f32_e32 v50, 1.0, v50
	v_rcp_f32_e32 v72, v50
	v_mul_f32_e32 v50, 0xbfb8aa3b, v57
	v_exp_f32_e32 v50, v50
	s_nop 0
	v_add_f32_e32 v50, 1.0, v50
	v_rcp_f32_e32 v73, v50
	s_nop 0
	v_pk_mul_f32 v[80:81], v[56:57], v[72:73]
	v_lshlrev_b32_e32 v72, 16, v51
	v_and_b32_e32 v73, 0xffff0000, v51
	v_pk_fma_f32 v[50:51], v[28:29], v[78:79], v[44:45]
	s_nop 0
	v_pk_fma_f32 v[50:51], v[32:33], v[68:69], v[50:51]
	s_nop 0
	v_pk_fma_f32 v[50:51], v[36:37], v[60:61], v[50:51]
	s_nop 0
	v_pk_fma_f32 v[50:51], v[40:41], v[72:73], v[50:51]
	s_nop 0
	v_mul_f32_e32 v56, 0xbfb8aa3b, v50
	v_mul_f32_e32 v57, 0xbfb8aa3b, v51
	v_exp_f32_e32 v56, v56
	v_exp_f32_e32 v57, v57
	v_add_f32_e32 v56, 1.0, v56
	v_add_f32_e32 v57, 1.0, v57
	v_rcp_f32_e32 v56, v56
	v_rcp_f32_e32 v57, v57
	s_nop 0
	v_pk_mul_f32 v[78:79], v[50:51], v[56:57]
	v_pk_fma_f32 v[50:51], v[2:3], v[76:77], v[18:19]
	v_lshlrev_b32_e32 v56, 16, v52
	v_pk_fma_f32 v[50:51], v[6:7], v[66:67], v[50:51]
	v_and_b32_e32 v57, 0xffff0000, v52
	v_pk_fma_f32 v[50:51], v[10:11], v[58:59], v[50:51]
	s_nop 0
	v_pk_fma_f32 v[50:51], v[14:15], v[56:57], v[50:51]
	s_nop 0
	v_mul_f32_e32 v52, 0xbfb8aa3b, v50
	v_exp_f32_e32 v52, v52
	s_nop 0
	v_add_f32_e32 v52, 1.0, v52
	v_rcp_f32_e32 v76, v52
	v_mul_f32_e32 v52, 0xbfb8aa3b, v51
	v_exp_f32_e32 v52, v52
	s_nop 0
	v_add_f32_e32 v52, 1.0, v52
	v_rcp_f32_e32 v77, v52
	s_nop 0
	v_pk_mul_f32 v[84:85], v[50:51], v[76:77]
	v_lshlrev_b32_e32 v50, 16, v53
	v_and_b32_e32 v51, 0xffff0000, v53
	v_pk_fma_f32 v[52:53], v[4:5], v[74:75], v[20:21]
	v_cvt_pk_bf16_f32 v76, v84, v85
	v_pk_fma_f32 v[52:53], v[8:9], v[64:65], v[52:53]
	s_nop 0
	v_pk_fma_f32 v[52:53], v[12:13], v[54:55], v[52:53]
	s_nop 0
	v_pk_fma_f32 v[52:53], v[16:17], v[50:51], v[52:53]
	s_nop 0
	v_mul_f32_e32 v74, 0xbfb8aa3b, v52
	v_mul_f32_e32 v75, 0xbfb8aa3b, v53
	v_exp_f32_e32 v74, v74
	v_exp_f32_e32 v75, v75
	v_add_f32_e32 v74, 1.0, v74
	v_add_f32_e32 v75, 1.0, v75
	v_rcp_f32_e32 v74, v74
	v_rcp_f32_e32 v75, v75
	s_nop 0
	v_pk_mul_f32 v[52:53], v[52:53], v[74:75]
	v_cvt_pk_bf16_f32 v74, v80, v81
	v_cvt_pk_bf16_f32 v75, v78, v79
	v_cvt_pk_bf16_f32 v77, v52, v53
	global_store_dwordx4 v[86:87], v[74:77], off nt
	ds_read_b32 v86, v98 offset:4116
	s_waitcnt lgkmcnt(0)
; __device__ __forceinline__ float silu_f(float v) { return v * __builtin_amdgcn_rcpf(1.0f + __builtin_amdgcn_exp2f(-1.44269504f * v)); }
; #define LAS __attribute__((address_space(3)))
; __device__ __forceinline__ unsigned pk2(float lo, float hi) { const cvt_f2 v = {lo, hi}; const cvt_b2 r = __builtin_convertvector(v, cvt_b2); return __builtin_bit_cast(unsigned, r); }
; __device__ __forceinline__ float silu_f(float v) { return v * __builtin_amdgcn_rcpf(1.0f + __builtin_amdgcn_exp2f(-1.44269504f * v)); }
;     ...
;     for (int j = 0; j < NT; ++j) { const v4u r = rr[j];
;         const float cur[8] = {bflo(r.x), bfhi(r.x), bflo(r.y), bfhi(r.y), bflo(r.z), bfhi(r.z), bflo(r.w), bfhi(r.w)}; float o[8];
; #pragma unroll
;         for (int e = 0; e < 8; ++e) { const float a = bias[e] + w[0][e] * h[0][e] + w[1][e] * h[1][e] + w[2][e] * h[2][e] + w[3][e] * cur[e]; o[e] = silu_f(a); h[0][e] = h[1][e]; h[1][e] = h[2][e]; h[2][e] = cur[e]; }
;         v4u pk; pk.x = pk2(o[0], o[1]); pk.y = pk2(o[2], o[3]); pk.z = pk2(o[4], o[5]); pk.w = pk2(o[6], o[7]);
;         __builtin_nontemporal_store(pk, (v4u*)(XC + (size_t)(row0 + j) * B_CD + ch));
;         if (TOLDS) { if (SCALE) { const float wg = wgt[j]; pk.x = pk2(o[0] * wg, o[1] * wg); pk.y = pk2(o[2] * wg, o[3] * wg); pk.z = pk2(o[4] * wg, o[5] * wg); pk.w = pk2(o[6] * wg, o[7] * wg); }
;             *(LAS v4u*)(ldst + j * lstride) = pk; }
	v_pk_mul_f32 v[52:53], v[52:53], v[86:87] op_sel_hi:[1,0]
	v_pk_mul_f32 v[74:75], v[80:81], v[86:87] op_sel_hi:[1,0]
	v_pk_mul_f32 v[76:77], v[78:79], v[86:87] op_sel_hi:[1,0]
	v_cvt_pk_bf16_f32 v74, v74, v75
	v_cvt_pk_bf16_f32 v75, v76, v77
	v_pk_mul_f32 v[76:77], v[84:85], v[86:87] op_sel_hi:[1,0]
	v_lshl_add_u64 v[80:81], v[108:109], 0, v[106:107]
	v_cvt_pk_bf16_f32 v76, v76, v77
	v_cvt_pk_bf16_f32 v77, v52, v53
	v_pk_fma_f32 v[52:53], v[26:27], v[70:71], v[42:43]
	ds_write_b128 v138, v[74:77] offset:48208
	v_pk_fma_f32 v[52:53], v[30:31], v[62:63], v[52:53]
	v_lshlrev_b32_e32 v74, 16, v46
	v_and_b32_e32 v75, 0xffff0000, v46
	v_pk_fma_f32 v[52:53], v[34:35], v[82:83], v[52:53]
	v_pk_fma_f32 v[26:27], v[26:27], v[62:63], v[42:43]
	v_pk_fma_f32 v[52:53], v[38:39], v[74:75], v[52:53]
	v_pk_fma_f32 v[26:27], v[30:31], v[82:83], v[26:27]
	v_mul_f32_e32 v46, 0xbfb8aa3b, v52
	v_exp_f32_e32 v46, v46
	v_pk_fma_f32 v[26:27], v[34:35], v[74:75], v[26:27]
	v_add_f32_e32 v46, 1.0, v46
	v_rcp_f32_e32 v70, v46
	v_mul_f32_e32 v46, 0xbfb8aa3b, v53
	v_exp_f32_e32 v46, v46
	s_nop 0
	v_add_f32_e32 v46, 1.0, v46
	v_rcp_f32_e32 v71, v46
	s_nop 0
	v_pk_mul_f32 v[76:77], v[52:53], v[70:71]
	v_lshlrev_b32_e32 v70, 16, v47
	v_and_b32_e32 v71, 0xffff0000, v47
	v_pk_fma_f32 v[46:47], v[28:29], v[68:69], v[44:45]
	v_pk_fma_f32 v[28:29], v[28:29], v[60:61], v[44:45]
	v_pk_fma_f32 v[46:47], v[32:33], v[60:61], v[46:47]
	v_pk_fma_f32 v[28:29], v[32:33], v[72:73], v[28:29]
	v_pk_fma_f32 v[46:47], v[36:37], v[72:73], v[46:47]
	v_pk_fma_f32 v[28:29], v[36:37], v[70:71], v[28:29]
	v_pk_fma_f32 v[46:47], v[40:41], v[70:71], v[46:47]
	s_nop 0
	v_mul_f32_e32 v52, 0xbfb8aa3b, v46
	v_mul_f32_e32 v53, 0xbfb8aa3b, v47
	v_exp_f32_e32 v52, v52
	v_exp_f32_e32 v53, v53
	v_add_f32_e32 v52, 1.0, v52
	v_add_f32_e32 v53, 1.0, v53
	v_rcp_f32_e32 v52, v52
	v_rcp_f32_e32 v53, v53
	s_nop 0
	v_pk_mul_f32 v[68:69], v[46:47], v[52:53]
	v_pk_fma_f32 v[46:47], v[2:3], v[66:67], v[18:19]
	v_lshlrev_b32_e32 v52, 16, v48
	v_pk_fma_f32 v[46:47], v[6:7], v[58:59], v[46:47]
	v_and_b32_e32 v53, 0xffff0000, v48
	v_pk_fma_f32 v[46:47], v[10:11], v[56:57], v[46:47]
	v_pk_fma_f32 v[2:3], v[2:3], v[58:59], v[18:19]
	v_pk_fma_f32 v[46:47], v[14:15], v[52:53], v[46:47]
	v_pk_fma_f32 v[2:3], v[6:7], v[56:57], v[2:3]
	v_mul_f32_e32 v48, 0xbfb8aa3b, v46
	v_exp_f32_e32 v48, v48
	v_pk_fma_f32 v[2:3], v[10:11], v[52:53], v[2:3]
	v_lshl_add_u64 v[10:11], v[108:109], 0, v[104:105]
	v_add_f32_e32 v48, 1.0, v48
	v_rcp_f32_e32 v66, v48
	v_mul_f32_e32 v48, 0xbfb8aa3b, v47
	v_exp_f32_e32 v48, v48
	s_nop 0
	v_add_f32_e32 v48, 1.0, v48
	v_rcp_f32_e32 v67, v48
	s_nop 0
	v_pk_mul_f32 v[78:79], v[46:47], v[66:67]
	v_lshlrev_b32_e32 v46, 16, v49
	v_and_b32_e32 v47, 0xffff0000, v49
	v_pk_fma_f32 v[48:49], v[4:5], v[64:65], v[20:21]
	v_cvt_pk_bf16_f32 v66, v78, v79
	v_pk_fma_f32 v[48:49], v[8:9], v[54:55], v[48:49]
	v_pk_fma_f32 v[4:5], v[4:5], v[54:55], v[20:21]
	v_pk_fma_f32 v[48:49], v[12:13], v[50:51], v[48:49]
	v_pk_fma_f32 v[4:5], v[8:9], v[50:51], v[4:5]
	v_pk_fma_f32 v[48:49], v[16:17], v[46:47], v[48:49]
	v_pk_fma_f32 v[4:5], v[12:13], v[46:47], v[4:5]
	v_mul_f32_e32 v64, 0xbfb8aa3b, v48
	v_mul_f32_e32 v65, 0xbfb8aa3b, v49
	v_exp_f32_e32 v64, v64
	v_exp_f32_e32 v65, v65
	v_add_f32_e32 v64, 1.0, v64
	v_add_f32_e32 v65, 1.0, v65
	v_rcp_f32_e32 v64, v64
	v_rcp_f32_e32 v65, v65
	s_nop 0
	v_pk_mul_f32 v[48:49], v[48:49], v[64:65]
	v_cvt_pk_bf16_f32 v64, v76, v77
	v_cvt_pk_bf16_f32 v65, v68, v69
	v_cvt_pk_bf16_f32 v67, v48, v49
	global_store_dwordx4 v[80:81], v[64:67], off nt
	ds_read_b32 v80, v98 offset:4120
	s_waitcnt lgkmcnt(0)
	v_pk_mul_f32 v[48:49], v[48:49], v[80:81] op_sel_hi:[1,0]
	v_pk_mul_f32 v[64:65], v[76:77], v[80:81] op_sel_hi:[1,0]
	v_pk_mul_f32 v[66:67], v[68:69], v[80:81] op_sel_hi:[1,0]
	v_cvt_pk_bf16_f32 v64, v64, v65
	v_cvt_pk_bf16_f32 v65, v66, v67
	v_pk_mul_f32 v[66:67], v[78:79], v[80:81] op_sel_hi:[1,0]
	s_nop 0
	v_cvt_pk_bf16_f32 v66, v66, v67
	v_cvt_pk_bf16_f32 v67, v48, v49
	v_lshlrev_b32_e32 v48, 16, v22
	v_and_b32_e32 v49, 0xffff0000, v22
	v_pk_fma_f32 v[26:27], v[38:39], v[48:49], v[26:27]
	ds_write_b128 v138, v[64:67] offset:49248
	v_mul_f32_e32 v22, 0xbfb8aa3b, v26
	v_exp_f32_e32 v22, v22
	s_nop 0
	v_add_f32_e32 v22, 1.0, v22
	v_rcp_f32_e32 v30, v22
	v_mul_f32_e32 v22, 0xbfb8aa3b, v27
	v_exp_f32_e32 v22, v22
	s_nop 0
	v_add_f32_e32 v22, 1.0, v22
	v_rcp_f32_e32 v31, v22
	v_lshlrev_b32_e32 v22, 16, v23
	v_and_b32_e32 v23, 0xffff0000, v23
	v_pk_fma_f32 v[22:23], v[40:41], v[22:23], v[28:29]
	v_pk_mul_f32 v[26:27], v[26:27], v[30:31]
	v_mul_f32_e32 v28, 0xbfb8aa3b, v22
	v_mul_f32_e32 v29, 0xbfb8aa3b, v23
	v_exp_f32_e32 v28, v28
	v_exp_f32_e32 v29, v29
	v_add_f32_e32 v28, 1.0, v28
	v_add_f32_e32 v29, 1.0, v29
	v_rcp_f32_e32 v28, v28
	v_rcp_f32_e32 v29, v29
	s_nop 0
	v_pk_mul_f32 v[22:23], v[22:23], v[28:29]
	v_lshlrev_b32_e32 v28, 16, v24
	v_and_b32_e32 v29, 0xffff0000, v24
	v_pk_fma_f32 v[2:3], v[14:15], v[28:29], v[2:3]
	s_nop 0
	v_mul_f32_e32 v6, 0xbfb8aa3b, v2
	v_mul_f32_e32 v7, 0xbfb8aa3b, v3
	v_exp_f32_e32 v6, v6
	v_exp_f32_e32 v7, v7
	v_add_f32_e32 v6, 1.0, v6
	v_add_f32_e32 v7, 1.0, v7
	v_rcp_f32_e32 v6, v6
	v_rcp_f32_e32 v7, v7
	s_nop 0
	v_pk_mul_f32 v[6:7], v[2:3], v[6:7]
	v_lshlrev_b32_e32 v2, 16, v25
	v_and_b32_e32 v3, 0xffff0000, v25
	v_pk_fma_f32 v[2:3], v[16:17], v[2:3], v[4:5]
	s_nop 0
	v_mul_f32_e32 v4, 0xbfb8aa3b, v2
	v_mul_f32_e32 v5, 0xbfb8aa3b, v3
	v_exp_f32_e32 v4, v4
	v_exp_f32_e32 v5, v5
	v_add_f32_e32 v4, 1.0, v4
	v_add_f32_e32 v5, 1.0, v5
	v_rcp_f32_e32 v4, v4
	v_rcp_f32_e32 v5, v5
	s_nop 0
	v_pk_mul_f32 v[8:9], v[2:3], v[4:5]
	v_cvt_pk_bf16_f32 v2, v26, v27
	v_cvt_pk_bf16_f32 v3, v22, v23
	v_cvt_pk_bf16_f32 v4, v6, v7
	v_cvt_pk_bf16_f32 v5, v8, v9
	global_store_dwordx4 v[10:11], v[2:5], off nt
	ds_read_b32 v10, v98 offset:4124
	s_waitcnt lgkmcnt(0)
	v_pk_mul_f32 v[2:3], v[26:27], v[10:11] op_sel_hi:[1,0]
	v_pk_mul_f32 v[4:5], v[22:23], v[10:11] op_sel_hi:[1,0]
	v_cvt_pk_bf16_f32 v2, v2, v3
	v_cvt_pk_bf16_f32 v3, v4, v5
	v_pk_mul_f32 v[4:5], v[6:7], v[10:11] op_sel_hi:[1,0]
	v_pk_mul_f32 v[6:7], v[8:9], v[10:11] op_sel_hi:[1,0]
	v_cvt_pk_bf16_f32 v4, v4, v5
	v_cvt_pk_bf16_f32 v5, v6, v7

; #define LAS __attribute__((address_space(3)))
;     float w[4][8], bias[8], h[3][8];
; #pragma unroll
;     for (int k = 0; k < 4; ++k) { const f32x4 a = *(const f32x4*)(F.b_conv_w + k * B_CD + ch), b = *(const f32x4*)(F.b_conv_w + k * B_CD + ch + 4);
;         w[k][0] = a.x; w[k][1] = a.y; w[k][2] = a.z; w[k][3] = a.w; w[k][4] = b.x; w[k][5] = b.y; w[k][6] = b.z; w[k][7] = b.w; }
;     { const f32x4 a = *(const f32x4*)(F.b_conv_b + ch), b = *(const f32x4*)(F.b_conv_b + ch + 4);
;       bias[0] = a.x; bias[1] = a.y; bias[2] = a.z; bias[3] = a.w; bias[4] = b.x; bias[5] = b.y; bias[6] = b.z; bias[7] = b.w; }
;     v4u rr[NT];
; #pragma unroll
;     for (int j = 0; j < NT; ++j) rr[j] = *(const v4u*)(XBC + (size_t)(row0 + j) * B_CD + ch);
; #pragma unroll
;     for (int k = 0; k < 3; ++k) {
;         if (hist_kind == 0) {
; #pragma unroll
;             for (int e = 0; e < 8; ++e) h[k][e] = 0.f;
;         } else if (hist_kind == 2) { const f32x4 a = *(const f32x4*)(hist + (size_t)k * B_CD + ch), b = *(const f32x4*)(hist + (size_t)k * B_CD + ch + 4);
;             h[k][0] = a.x; h[k][1] = a.y; h[k][2] = a.z; h[k][3] = a.w; h[k][4] = b.x; h[k][5] = b.y; h[k][6] = b.z; h[k][7] = b.w;
;         } else { const v4u r = *(const v4u*)(XBC + (size_t)(row0 - 3 + k) * B_CD + ch);
;             h[k][0] = bflo(r.x); h[k][1] = bfhi(r.x); h[k][2] = bflo(r.y); h[k][3] = bfhi(r.y); h[k][4] = bflo(r.z); h[k][5] = bfhi(r.z); h[k][6] = bflo(r.w); h[k][7] = bfhi(r.w); }
;     }
; __device__ __forceinline__ void ssd_states_phase(Frame& F) {
;     ...
;         { const bool isC = tid >= 256; const int t2 = tid & 255, tg = t2 >> 4, oct = t2 & 15; LAS unsigned char* ld = L + SSD_BM + (4 * tg) * SSD_BST + oct * 16;
;           if (4 * tg < ntok) { if (isC) conv_item<false, false, 4>(F, XBCr, XCw, 5120 + g * 128 + oct * 8, tok0 + 4 * tg, tg == 0 ? hk : 1, hist, ld, SSD_BST, WGT);
;                                else conv_item<false, true, 4>(F, XBCr, XCw, 4096 + g * 128 + oct * 8, tok0 + 4 * tg, tg == 0 ? hk : 1, hist, ld, SSD_BST, WGT); }
.LBB0_1144:
	s_andn2_saveexec_b64 s[78:79], s[0:1]
	s_cbranch_execz .LBB0_1186
	s_lshl_b32 s0, s65, 7
	v_lshl_or_b32 v4, v94, 3, s0
	v_cmp_eq_u32_e64 s[0:1], 0, v2
	v_add_u32_e32 v95, s71, v3
	s_nop 0
	v_cndmask_b32_e64 v96, 1, v137, s[0:1]
	s_and_saveexec_b64 s[0:1], vcc
	s_xor_b64 s[0:1], exec, s[0:1]
	s_cbranch_execz .LBB0_1165
	v_or_b32_e32 v22, 0x1000, v4
	v_readlane_b32 s4, v251, 2
	v_lshlrev_b32_e32 v98, 2, v22
	v_readlane_b32 s18, v251, 16
	v_readlane_b32 s19, v251, 17
	v_readlane_b32 s5, v251, 3
	v_readlane_b32 s6, v251, 4
	v_lshl_add_u64 v[14:15], s[18:19], 0, v[98:99]
	v_add_co_u32_e32 v8, vcc, 0x6000, v14
	v_readlane_b32 s7, v251, 5
	s_nop 0
	v_addc_co_u32_e32 v9, vcc, 0, v15, vcc
	v_add_co_u32_e32 v12, vcc, 0xc000, v14
	v_readlane_b32 s8, v251, 6
	v_readlane_b32 s9, v251, 7
	v_readlane_b32 s10, v251, 8
	v_readlane_b32 s11, v251, 9
	v_readlane_b32 s12, v251, 10
	v_readlane_b32 s13, v251, 11
	v_readlane_b32 s14, v251, 12
	v_readlane_b32 s15, v251, 13
	v_readlane_b32 s16, v251, 14
	v_readlane_b32 s17, v251, 15
	v_addc_co_u32_e32 v13, vcc, 0, v15, vcc
	v_lshlrev_b32_e32 v86, 1, v22
	v_mov_b32_e32 v87, v99
	global_load_dwordx4 v[2:5], v98, s[18:19] offset:16
	global_load_dwordx4 v[26:29], v98, s[18:19]
	v_lshl_add_u64 v[6:7], v[14:15], 0, s[30:31]
	v_lshl_add_u64 v[10:11], v[14:15], 0, s[34:35]
	v_lshl_add_u64 v[16:17], v[14:15], 0, s[76:77]
	v_add_co_u32_e32 v14, vcc, 0x12000, v14
	v_readlane_b32 s4, v251, 26
	v_lshl_add_u64 v[90:91], s[20:21], 0, v[86:87]
	v_or_b32_e32 v54, 1, v95
	v_addc_co_u32_e32 v15, vcc, 0, v15, vcc
	v_readlane_b32 s5, v251, 27
	v_mad_i64_i32 v[22:23], s[2:3], v95, s56, v[90:91]
	v_mad_i64_i32 v[24:25], s[2:3], v54, s56, v[90:91]
	v_or_b32_e32 v55, 2, v95
	v_or_b32_e32 v58, 3, v95
	global_load_dwordx4 v[30:33], v[8:9], off
	s_nop 0
	global_load_dwordx4 v[6:9], v[6:7], off offset:16
	s_nop 0
	global_load_dwordx4 v[34:37], v[12:13], off
	s_nop 0
	global_load_dwordx4 v[10:13], v[10:11], off offset:16
	s_nop 0
	global_load_dwordx4 v[38:41], v[14:15], off
	s_nop 0
	global_load_dwordx4 v[14:17], v[16:17], off offset:16
	s_nop 0
	global_load_dwordx4 v[18:21], v98, s[4:5] offset:16
	global_load_dwordx4 v[42:45], v98, s[4:5]
	global_load_dwordx4 v[66:69], v[22:23], off
	global_load_dwordx4 v[50:53], v[24:25], off
	v_mad_i64_i32 v[22:23], s[2:3], v55, s56, v[90:91]
	v_mad_i64_i32 v[24:25], s[2:3], v58, s56, v[90:91]
	global_load_dwordx4 v[46:49], v[22:23], off
	s_nop 0
	global_load_dwordx4 v[22:25], v[24:25], off
	v_lshl_add_u64 v[56:57], s[36:37], 0, v[98:99]
	v_cmp_lt_i32_e32 vcc, 1, v96
	v_readlane_b32 s6, v251, 28
	v_readlane_b32 s7, v251, 29
	v_readlane_b32 s8, v251, 30
	v_readlane_b32 s9, v251, 31
	v_readlane_b32 s10, v251, 32
	v_readlane_b32 s11, v251, 33
	v_readlane_b32 s12, v251, 34
	v_readlane_b32 s13, v251, 35
	v_readlane_b32 s14, v251, 36
	v_readlane_b32 s15, v251, 37
	v_readlane_b32 s16, v251, 38
	v_readlane_b32 s17, v251, 39
	v_readlane_b32 s18, v251, 40
	v_readlane_b32 s19, v251, 41
	v_cmp_ne_u32_e32 vcc, 1, v96
	s_cbranch_vccnz .Lp7_slow_1
	v_add_u32_e32 v59, -3, v95
	v_mad_i64_i32 v[60:61], s[72:73], v59, s56, v[90:91]
	global_load_dwordx4 v[200:203], v[60:61], off
	v_mad_i64_i32 v[92:93], s[2:3], v95, s56, 0
	v_mad_i64_i32 v[88:89], s[2:3], v54, s56, 0
	v_mad_i64_i32 v[84:85], s[2:3], v55, s56, 0
	v_mad_i64_i32 v[82:83], s[2:3], v58, s56, 0
	v_add_u32_e32 v54, -2, v95
	v_mad_i64_i32 v[54:55], s[72:73], v54, s56, v[90:91]
	global_load_dwordx4 v[204:207], v[54:55], off
	v_add_u32_e32 v54, -1, v95
	v_mad_i64_i32 v[54:55], s[72:73], v54, s56, v[90:91]
	global_load_dwordx4 v[208:211], v[54:55], off
	s_waitcnt vmcnt(0)
	v_lshlrev_b32_e32 v78, 16, v200
	v_and_b32_e32 v79, 0xffff0000, v200
	v_lshlrev_b32_e32 v80, 16, v201
	v_and_b32_e32 v81, 0xffff0000, v201
	v_lshlrev_b32_e32 v70, 16, v202
	v_and_b32_e32 v71, 0xffff0000, v202
	v_lshlrev_b32_e32 v72, 16, v203
	v_and_b32_e32 v73, 0xffff0000, v203
	v_lshlrev_b32_e32 v74, 16, v204
	v_and_b32_e32 v75, 0xffff0000, v204
	v_lshlrev_b32_e32 v76, 16, v205
	v_and_b32_e32 v77, 0xffff0000, v205
	v_lshlrev_b32_e32 v58, 16, v206
	v_and_b32_e32 v59, 0xffff0000, v206
	v_lshlrev_b32_e32 v60, 16, v207
	v_and_b32_e32 v61, 0xffff0000, v207
	v_lshlrev_b32_e32 v62, 16, v208
	v_and_b32_e32 v63, 0xffff0000, v208
	v_lshlrev_b32_e32 v64, 16, v209
	v_and_b32_e32 v65, 0xffff0000, v209
	v_lshlrev_b32_e32 v54, 16, v210
	v_and_b32_e32 v55, 0xffff0000, v210
	v_lshlrev_b32_e32 v56, 16, v211
	v_and_b32_e32 v57, 0xffff0000, v211
	s_branch .Lp7_join_1
.Lp7_slow_1:
	v_cmp_lt_i32_e32 vcc, 1, v96
	s_and_saveexec_b64 s[2:3], vcc
	s_xor_b64 s[2:3], exec, s[2:3]
	s_cbranch_execz .LBB0_1148
	global_load_dwordx4 v[70:73], v[56:57], off offset:16
	global_load_dwordx4 v[78:81], v[56:57], off

; __device__ __forceinline__ float silu_f(float v) { return v * __builtin_amdgcn_rcpf(1.0f + __builtin_amdgcn_exp2f(-1.44269504f * v)); }
; #define LAS __attribute__((address_space(3)))
; __device__ __forceinline__ unsigned pk2(float lo, float hi) { const cvt_f2 v = {lo, hi}; const cvt_b2 r = __builtin_convertvector(v, cvt_b2); return __builtin_bit_cast(unsigned, r); }
; __device__ __forceinline__ float silu_f(float v) { return v * __builtin_amdgcn_rcpf(1.0f + __builtin_amdgcn_exp2f(-1.44269504f * v)); }
;     ...
; #pragma unroll
;     for (int j = 0; j < NT; ++j) { const v4u r = rr[j];
;         const float cur[8] = {bflo(r.x), bfhi(r.x), bflo(r.y), bfhi(r.y), bflo(r.z), bfhi(r.z), bflo(r.w), bfhi(r.w)}; float o[8];
; #pragma unroll
;         for (int e = 0; e < 8; ++e) { const float a = bias[e] + w[0][e] * h[0][e] + w[1][e] * h[1][e] + w[2][e] * h[2][e] + w[3][e] * cur[e]; o[e] = silu_f(a); h[0][e] = h[1][e]; h[1][e] = h[2][e]; h[2][e] = cur[e]; }
;         v4u pk; pk.x = pk2(o[0], o[1]); pk.y = pk2(o[2], o[3]); pk.z = pk2(o[4], o[5]); pk.w = pk2(o[6], o[7]);
;         __builtin_nontemporal_store(pk, (v4u*)(XC + (size_t)(row0 + j) * B_CD + ch));
;         if (TOLDS) { if (SCALE) { const float wg = wgt[j]; pk.x = pk2(o[0] * wg, o[1] * wg); pk.y = pk2(o[2] * wg, o[3] * wg); pk.z = pk2(o[4] * wg, o[5] * wg); pk.w = pk2(o[6] * wg, o[7] * wg); }
;             *(LAS v4u*)(ldst + j * lstride) = pk; }
.Lp7_join_1:
	s_waitcnt vmcnt(0)
	v_pk_fma_f32 v[78:79], v[26:27], v[78:79], v[42:43]
	v_lshlrev_b32_e32 v90, 16, v66
	v_pk_fma_f32 v[78:79], v[30:31], v[74:75], v[78:79]
	v_and_b32_e32 v91, 0xffff0000, v66
	v_pk_fma_f32 v[78:79], v[34:35], v[62:63], v[78:79]
	v_pk_fma_f32 v[70:71], v[2:3], v[70:71], v[18:19]
	v_pk_fma_f32 v[78:79], v[38:39], v[90:91], v[78:79]
	v_pk_fma_f32 v[70:71], v[6:7], v[58:59], v[70:71]
	v_mul_f32_e32 v66, 0xbfb8aa3b, v78
	v_exp_f32_e32 v66, v66
	v_pk_fma_f32 v[70:71], v[10:11], v[54:55], v[70:71]
	v_mov_b32_e32 v87, v99
	v_lshl_add_u64 v[86:87], s[22:23], 0, v[86:87]
	v_add_f32_e32 v66, 1.0, v66
	v_rcp_f32_e32 v106, v66
	v_mul_f32_e32 v66, 0xbfb8aa3b, v79
	v_exp_f32_e32 v66, v66
	s_nop 0
	v_add_f32_e32 v66, 1.0, v66
	v_rcp_f32_e32 v107, v66
	v_lshlrev_b32_e32 v66, 16, v67
	v_and_b32_e32 v67, 0xffff0000, v67
	v_pk_mul_f32 v[106:107], v[78:79], v[106:107]
	v_pk_fma_f32 v[78:79], v[28:29], v[80:81], v[44:45]
	s_nop 0
	v_pk_fma_f32 v[78:79], v[32:33], v[76:77], v[78:79]
	s_nop 0
	v_pk_fma_f32 v[78:79], v[36:37], v[64:65], v[78:79]
	s_nop 0
	v_pk_fma_f32 v[78:79], v[40:41], v[66:67], v[78:79]
	s_nop 0
	v_mul_f32_e32 v80, 0xbfb8aa3b, v78
	v_mul_f32_e32 v81, 0xbfb8aa3b, v79
	v_exp_f32_e32 v80, v80
	v_exp_f32_e32 v81, v81
	v_add_f32_e32 v80, 1.0, v80
	v_add_f32_e32 v81, 1.0, v81
	v_rcp_f32_e32 v80, v80
	v_rcp_f32_e32 v81, v81
	s_nop 0
	v_pk_mul_f32 v[80:81], v[78:79], v[80:81]
	v_lshlrev_b32_e32 v78, 16, v68
	v_and_b32_e32 v79, 0xffff0000, v68
	v_pk_fma_f32 v[70:71], v[14:15], v[78:79], v[70:71]
	s_nop 0
	v_mul_f32_e32 v68, 0xbfb8aa3b, v70
	v_exp_f32_e32 v68, v68
	s_nop 0
	v_add_f32_e32 v68, 1.0, v68
	v_rcp_f32_e32 v108, v68
	v_mul_f32_e32 v68, 0xbfb8aa3b, v71
	v_exp_f32_e32 v68, v68
	s_nop 0
	v_add_f32_e32 v68, 1.0, v68
	v_rcp_f32_e32 v109, v68
	v_lshlrev_b32_e32 v68, 16, v69
	v_and_b32_e32 v69, 0xffff0000, v69
	v_pk_mul_f32 v[108:109], v[70:71], v[108:109]
	v_pk_fma_f32 v[70:71], v[4:5], v[72:73], v[20:21]
	s_nop 0
	v_pk_fma_f32 v[70:71], v[8:9], v[60:61], v[70:71]
	s_nop 0
	v_pk_fma_f32 v[70:71], v[12:13], v[56:57], v[70:71]
	s_nop 0
	v_pk_fma_f32 v[70:71], v[16:17], v[68:69], v[70:71]
	s_nop 0
	v_mul_f32_e32 v72, 0xbfb8aa3b, v70
	v_mul_f32_e32 v73, 0xbfb8aa3b, v71
	v_exp_f32_e32 v72, v72
	v_exp_f32_e32 v73, v73
	v_add_f32_e32 v72, 1.0, v72
	v_add_f32_e32 v73, 1.0, v73
	v_rcp_f32_e32 v72, v72
	v_rcp_f32_e32 v73, v73
	s_nop 0
	v_pk_mul_f32 v[110:111], v[70:71], v[72:73]
	v_cvt_pk_bf16_f32 v70, v106, v107
	v_cvt_pk_bf16_f32 v71, v80, v81
	v_cvt_pk_bf16_f32 v72, v108, v109
	v_cvt_pk_bf16_f32 v73, v110, v111
	v_lshl_add_u64 v[80:81], v[86:87], 0, v[92:93]
	v_add_u32_e32 v92, v97, v104
	global_store_dwordx4 v[80:81], v[70:73], off nt
	ds_write_b128 v92, v[70:73] offset:8192
	v_lshlrev_b32_e32 v80, 16, v50
	v_pk_fma_f32 v[70:71], v[26:27], v[74:75], v[42:43]
	v_and_b32_e32 v81, 0xffff0000, v50
	v_pk_fma_f32 v[70:71], v[30:31], v[62:63], v[70:71]
	s_nop 0
	v_pk_fma_f32 v[70:71], v[34:35], v[90:91], v[70:71]
	s_nop 0
	v_pk_fma_f32 v[70:71], v[38:39], v[80:81], v[70:71]
	s_nop 0
	v_mul_f32_e32 v50, 0xbfb8aa3b, v70
	v_exp_f32_e32 v50, v50
	s_nop 0
	v_add_f32_e32 v50, 1.0, v50
	v_rcp_f32_e32 v72, v50
	v_mul_f32_e32 v50, 0xbfb8aa3b, v71
	v_exp_f32_e32 v50, v50
	s_nop 0
	v_add_f32_e32 v50, 1.0, v50
	v_rcp_f32_e32 v73, v50
	s_nop 0
	v_pk_mul_f32 v[74:75], v[70:71], v[72:73]
	v_lshlrev_b32_e32 v72, 16, v51
	v_and_b32_e32 v73, 0xffff0000, v51
	v_pk_fma_f32 v[50:51], v[28:29], v[76:77], v[44:45]
	s_nop 0
	v_pk_fma_f32 v[50:51], v[32:33], v[64:65], v[50:51]
	s_nop 0
	v_pk_fma_f32 v[50:51], v[36:37], v[66:67], v[50:51]
	s_nop 0
	v_pk_fma_f32 v[50:51], v[40:41], v[72:73], v[50:51]
	s_nop 0
	v_mul_f32_e32 v70, 0xbfb8aa3b, v50
	v_mul_f32_e32 v71, 0xbfb8aa3b, v51
	v_exp_f32_e32 v70, v70
	v_exp_f32_e32 v71, v71
	v_add_f32_e32 v70, 1.0, v70
	v_add_f32_e32 v71, 1.0, v71
	v_rcp_f32_e32 v70, v70
	v_rcp_f32_e32 v71, v71
	s_nop 0
	v_pk_mul_f32 v[76:77], v[50:51], v[70:71]
	v_pk_fma_f32 v[50:51], v[2:3], v[58:59], v[18:19]
	v_lshlrev_b32_e32 v70, 16, v52
	v_pk_fma_f32 v[50:51], v[6:7], v[54:55], v[50:51]
	v_and_b32_e32 v71, 0xffff0000, v52
	v_pk_fma_f32 v[50:51], v[10:11], v[78:79], v[50:51]
	s_nop 0
	v_pk_fma_f32 v[50:51], v[14:15], v[70:71], v[50:51]
	s_nop 0
	v_mul_f32_e32 v52, 0xbfb8aa3b, v50
	v_exp_f32_e32 v52, v52
	s_nop 0
	v_add_f32_e32 v52, 1.0, v52
	v_rcp_f32_e32 v58, v52
	v_mul_f32_e32 v52, 0xbfb8aa3b, v51
	v_exp_f32_e32 v52, v52
	s_nop 0
	v_add_f32_e32 v52, 1.0, v52
	v_rcp_f32_e32 v59, v52
	s_nop 0
	v_pk_mul_f32 v[96:97], v[50:51], v[58:59]
	v_lshlrev_b32_e32 v50, 16, v53
	v_and_b32_e32 v51, 0xffff0000, v53
	v_pk_fma_f32 v[52:53], v[4:5], v[60:61], v[20:21]
	v_cvt_pk_bf16_f32 v60, v96, v97
	v_pk_fma_f32 v[52:53], v[8:9], v[56:57], v[52:53]
	s_nop 0
	v_pk_fma_f32 v[52:53], v[12:13], v[68:69], v[52:53]
	s_nop 0
	v_pk_fma_f32 v[52:53], v[16:17], v[50:51], v[52:53]
	s_nop 0
	v_mul_f32_e32 v58, 0xbfb8aa3b, v52
	v_mul_f32_e32 v59, 0xbfb8aa3b, v53
	v_exp_f32_e32 v58, v58
	v_exp_f32_e32 v59, v59
	v_add_f32_e32 v58, 1.0, v58
	v_add_f32_e32 v59, 1.0, v59
	v_rcp_f32_e32 v58, v58
	v_rcp_f32_e32 v59, v59
	s_nop 0
	v_pk_mul_f32 v[52:53], v[52:53], v[58:59]
	v_cvt_pk_bf16_f32 v58, v74, v75
	v_cvt_pk_bf16_f32 v59, v76, v77
	v_cvt_pk_bf16_f32 v61, v52, v53
	v_lshl_add_u64 v[52:53], v[86:87], 0, v[88:89]
	global_store_dwordx4 v[52:53], v[58:61], off nt
	ds_write_b128 v92, v[58:61] offset:8464
	v_lshlrev_b32_e32 v52, 16, v46
	v_pk_fma_f32 v[58:59], v[26:27], v[62:63], v[42:43]
	v_and_b32_e32 v53, 0xffff0000, v46
	v_pk_fma_f32 v[58:59], v[30:31], v[90:91], v[58:59]
	v_lshlrev_b32_e32 v74, 16, v49
	v_pk_fma_f32 v[58:59], v[34:35], v[80:81], v[58:59]
; __device__ __forceinline__ float silu_f(float v) { return v * __builtin_amdgcn_rcpf(1.0f + __builtin_amdgcn_exp2f(-1.44269504f * v)); }
; __device__ __forceinline__ unsigned pk2(float lo, float hi) { const cvt_f2 v = {lo, hi}; const cvt_b2 r = __builtin_convertvector(v, cvt_b2); return __builtin_bit_cast(unsigned, r); }
; __device__ __forceinline__ float silu_f(float v) { return v * __builtin_amdgcn_rcpf(1.0f + __builtin_amdgcn_exp2f(-1.44269504f * v)); }
;     ...
;     for (int j = 0; j < NT; ++j) { const v4u r = rr[j];
;         const float cur[8] = {bflo(r.x), bfhi(r.x), bflo(r.y), bfhi(r.y), bflo(r.z), bfhi(r.z), bflo(r.w), bfhi(r.w)}; float o[8];
; #pragma unroll
;         for (int e = 0; e < 8; ++e) { const float a = bias[e] + w[0][e] * h[0][e] + w[1][e] * h[1][e] + w[2][e] * h[2][e] + w[3][e] * cur[e]; o[e] = silu_f(a); h[0][e] = h[1][e]; h[1][e] = h[2][e]; h[2][e] = cur[e]; }
;         v4u pk; pk.x = pk2(o[0], o[1]); pk.y = pk2(o[2], o[3]); pk.z = pk2(o[4], o[5]); pk.w = pk2(o[6], o[7]);
;         __builtin_nontemporal_store(pk, (v4u*)(XC + (size_t)(row0 + j) * B_CD + ch));
	v_and_b32_e32 v75, 0xffff0000, v49
	v_pk_fma_f32 v[58:59], v[38:39], v[52:53], v[58:59]
	v_pk_fma_f32 v[26:27], v[26:27], v[90:91], v[42:43]
	v_mul_f32_e32 v46, 0xbfb8aa3b, v58
	v_exp_f32_e32 v46, v46
	v_pk_fma_f32 v[26:27], v[30:31], v[80:81], v[26:27]
	v_add_f32_e32 v46, 1.0, v46
	v_rcp_f32_e32 v60, v46
	v_mul_f32_e32 v46, 0xbfb8aa3b, v59
	v_exp_f32_e32 v46, v46
	v_pk_fma_f32 v[26:27], v[34:35], v[52:53], v[26:27]
	v_add_f32_e32 v46, 1.0, v46
	v_rcp_f32_e32 v61, v46
	s_nop 0
	v_pk_mul_f32 v[58:59], v[58:59], v[60:61]
	v_lshlrev_b32_e32 v60, 16, v47
	v_and_b32_e32 v61, 0xffff0000, v47
	v_pk_fma_f32 v[46:47], v[28:29], v[64:65], v[44:45]
	v_lshlrev_b32_e32 v64, 16, v48
	v_pk_fma_f32 v[46:47], v[32:33], v[66:67], v[46:47]
	v_and_b32_e32 v65, 0xffff0000, v48
	v_pk_fma_f32 v[46:47], v[36:37], v[72:73], v[46:47]
	v_pk_fma_f32 v[28:29], v[28:29], v[66:67], v[44:45]
	v_pk_fma_f32 v[46:47], v[40:41], v[60:61], v[46:47]
	v_pk_fma_f32 v[28:29], v[32:33], v[72:73], v[28:29]
	v_mul_f32_e32 v62, 0xbfb8aa3b, v46
	v_mul_f32_e32 v63, 0xbfb8aa3b, v47
	v_exp_f32_e32 v62, v62
	v_exp_f32_e32 v63, v63
	v_pk_fma_f32 v[28:29], v[36:37], v[60:61], v[28:29]
	v_add_f32_e32 v62, 1.0, v62
	v_add_f32_e32 v63, 1.0, v63
	v_rcp_f32_e32 v62, v62
	v_rcp_f32_e32 v63, v63
	s_nop 0
	v_pk_mul_f32 v[62:63], v[46:47], v[62:63]
	v_pk_fma_f32 v[46:47], v[2:3], v[54:55], v[18:19]
	v_pk_fma_f32 v[2:3], v[2:3], v[78:79], v[18:19]
	v_pk_fma_f32 v[46:47], v[6:7], v[78:79], v[46:47]
	v_pk_fma_f32 v[2:3], v[6:7], v[70:71], v[2:3]
	v_pk_fma_f32 v[46:47], v[10:11], v[70:71], v[46:47]
	v_pk_fma_f32 v[2:3], v[10:11], v[64:65], v[2:3]
	v_pk_fma_f32 v[46:47], v[14:15], v[64:65], v[46:47]
	s_nop 0
	v_mul_f32_e32 v48, 0xbfb8aa3b, v46
	v_exp_f32_e32 v48, v48
	s_nop 0
	v_add_f32_e32 v48, 1.0, v48
	v_rcp_f32_e32 v54, v48
	v_mul_f32_e32 v48, 0xbfb8aa3b, v47
	v_exp_f32_e32 v48, v48
	s_nop 0
	v_add_f32_e32 v48, 1.0, v48
	v_rcp_f32_e32 v55, v48
	s_nop 0
	v_pk_mul_f32 v[54:55], v[46:47], v[54:55]
	v_pk_fma_f32 v[46:47], v[4:5], v[56:57], v[20:21]
	v_pk_fma_f32 v[4:5], v[4:5], v[68:69], v[20:21]
	v_pk_fma_f32 v[46:47], v[8:9], v[68:69], v[46:47]
	v_pk_fma_f32 v[4:5], v[8:9], v[50:51], v[4:5]
	v_pk_fma_f32 v[46:47], v[12:13], v[50:51], v[46:47]
	v_pk_fma_f32 v[4:5], v[12:13], v[74:75], v[4:5]
	v_pk_fma_f32 v[46:47], v[16:17], v[74:75], v[46:47]
	s_nop 0
	v_mul_f32_e32 v48, 0xbfb8aa3b, v46
	v_mul_f32_e32 v49, 0xbfb8aa3b, v47
	v_exp_f32_e32 v48, v48
	v_exp_f32_e32 v49, v49
	v_add_f32_e32 v48, 1.0, v48
	v_add_f32_e32 v49, 1.0, v49
	v_rcp_f32_e32 v48, v48
	v_rcp_f32_e32 v49, v49
	s_nop 0
	v_pk_mul_f32 v[56:57], v[46:47], v[48:49]
	v_cvt_pk_bf16_f32 v46, v58, v59
	v_cvt_pk_bf16_f32 v47, v62, v63
	v_cvt_pk_bf16_f32 v48, v54, v55
	v_cvt_pk_bf16_f32 v49, v56, v57
	v_lshl_add_u64 v[54:55], v[86:87], 0, v[84:85]
	global_store_dwordx4 v[54:55], v[46:49], off nt
	ds_write_b128 v92, v[46:49] offset:8736
	s_nop 0
	v_lshlrev_b32_e32 v46, 16, v22
	v_and_b32_e32 v47, 0xffff0000, v22
	v_pk_fma_f32 v[26:27], v[38:39], v[46:47], v[26:27]
	s_nop 0
	v_mul_f32_e32 v22, 0xbfb8aa3b, v26
	v_exp_f32_e32 v22, v22
	s_nop 0
	v_add_f32_e32 v22, 1.0, v22
	v_rcp_f32_e32 v30, v22
	v_mul_f32_e32 v22, 0xbfb8aa3b, v27
	v_exp_f32_e32 v22, v22
	s_nop 0
	v_add_f32_e32 v22, 1.0, v22
	v_rcp_f32_e32 v31, v22
	v_lshlrev_b32_e32 v22, 16, v23
	v_and_b32_e32 v23, 0xffff0000, v23
	v_pk_fma_f32 v[22:23], v[40:41], v[22:23], v[28:29]
	v_pk_mul_f32 v[26:27], v[26:27], v[30:31]
	v_mul_f32_e32 v28, 0xbfb8aa3b, v22
	v_mul_f32_e32 v29, 0xbfb8aa3b, v23
	v_exp_f32_e32 v28, v28
	v_exp_f32_e32 v29, v29
	v_add_f32_e32 v28, 1.0, v28
	v_add_f32_e32 v29, 1.0, v29
	v_rcp_f32_e32 v28, v28
	v_rcp_f32_e32 v29, v29
	s_nop 0
	v_pk_mul_f32 v[22:23], v[22:23], v[28:29]
	v_lshlrev_b32_e32 v28, 16, v24
	v_and_b32_e32 v29, 0xffff0000, v24
	v_pk_fma_f32 v[2:3], v[14:15], v[28:29], v[2:3]
	s_nop 0
	v_mul_f32_e32 v6, 0xbfb8aa3b, v2
	v_mul_f32_e32 v7, 0xbfb8aa3b, v3
	v_exp_f32_e32 v6, v6
	v_exp_f32_e32 v7, v7
	v_add_f32_e32 v6, 1.0, v6
	v_add_f32_e32 v7, 1.0, v7
	v_rcp_f32_e32 v6, v6
	v_rcp_f32_e32 v7, v7
	s_nop 0
	v_pk_mul_f32 v[6:7], v[2:3], v[6:7]
	v_lshlrev_b32_e32 v2, 16, v25
	v_and_b32_e32 v3, 0xffff0000, v25
	v_pk_fma_f32 v[2:3], v[16:17], v[2:3], v[4:5]
	s_nop 0
	v_mul_f32_e32 v4, 0xbfb8aa3b, v2
	v_mul_f32_e32 v5, 0xbfb8aa3b, v3
	v_exp_f32_e32 v4, v4
	v_exp_f32_e32 v5, v5
	v_add_f32_e32 v4, 1.0, v4
	v_add_f32_e32 v5, 1.0, v5
	v_rcp_f32_e32 v4, v4
	v_rcp_f32_e32 v5, v5
	s_nop 0
	v_pk_mul_f32 v[8:9], v[2:3], v[4:5]
	v_cvt_pk_bf16_f32 v2, v26, v27
	v_cvt_pk_bf16_f32 v3, v22, v23
	v_cvt_pk_bf16_f32 v4, v6, v7
	v_cvt_pk_bf16_f32 v5, v8, v9
	v_lshl_add_u64 v[6:7], v[86:87], 0, v[82:83]
	global_store_dwordx4 v[6:7], v[2:5], off nt
	ds_write_b128 v92, v[2:5] offset:9008
;     float w[4][8], bias[8], h[3][8];
; #pragma unroll
;     for (int k = 0; k < 4; ++k) { const f32x4 a = *(const f32x4*)(F.b_conv_w + k * B_CD + ch), b = *(const f32x4*)(F.b_conv_w + k * B_CD + ch + 4);
;         w[k][0] = a.x; w[k][1] = a.y; w[k][2] = a.z; w[k][3] = a.w; w[k][4] = b.x; w[k][5] = b.y; w[k][6] = b.z; w[k][7] = b.w; }
;     { const f32x4 a = *(const f32x4*)(F.b_conv_b + ch), b = *(const f32x4*)(F.b_conv_b + ch + 4);
;       bias[0] = a.x; bias[1] = a.y; bias[2] = a.z; bias[3] = a.w; bias[4] = b.x; bias[5] = b.y; bias[6] = b.z; bias[7] = b.w; }
;     v4u rr[NT];
; #pragma unroll
;     for (int j = 0; j < NT; ++j) rr[j] = *(const v4u*)(XBC + (size_t)(row0 + j) * B_CD + ch);
; #pragma unroll
;     for (int k = 0; k < 3; ++k) {
;         if (hist_kind == 0) {
; #pragma unroll
;             for (int e = 0; e < 8; ++e) h[k][e] = 0.f;
;         } else if (hist_kind == 2) { const f32x4 a = *(const f32x4*)(hist + (size_t)k * B_CD + ch), b = *(const f32x4*)(hist + (size_t)k * B_CD + ch + 4);
;             h[k][0] = a.x; h[k][1] = a.y; h[k][2] = a.z; h[k][3] = a.w; h[k][4] = b.x; h[k][5] = b.y; h[k][6] = b.z; h[k][7] = b.w;
;         } else { const v4u r = *(const v4u*)(XBC + (size_t)(row0 - 3 + k) * B_CD + ch);
;             h[k][0] = bflo(r.x); h[k][1] = bfhi(r.x); h[k][2] = bflo(r.y); h[k][3] = bfhi(r.y); h[k][4] = bflo(r.z); h[k][5] = bfhi(r.z); h[k][6] = bflo(r.w); h[k][7] = bfhi(r.w); }
;     }
; __device__ __forceinline__ void ssd_states_phase(Frame& F) {
;     ...
;           if (4 * tg < ntok) { if (isC) conv_item<false, false, 4>(F, XBCr, XCw, 5120 + g * 128 + oct * 8, tok0 + 4 * tg, tg == 0 ? hk : 1, hist, ld, SSD_BST, WGT);
.LBB0_1165:
	s_andn2_saveexec_b64 s[0:1], s[0:1]
	s_cbranch_execz .LBB0_1185
	v_or_b32_e32 v22, 0x1400, v4
	v_readlane_b32 s4, v251, 2
	v_lshlrev_b32_e32 v98, 2, v22
	v_readlane_b32 s18, v251, 16
	v_readlane_b32 s19, v251, 17
	v_readlane_b32 s5, v251, 3
	v_readlane_b32 s6, v251, 4
	v_lshl_add_u64 v[14:15], s[18:19], 0, v[98:99]
	v_add_co_u32_e32 v8, vcc, 0x6000, v14
	v_readlane_b32 s7, v251, 5
	s_nop 0
	v_addc_co_u32_e32 v9, vcc, 0, v15, vcc
	v_add_co_u32_e32 v12, vcc, 0xc000, v14
	v_readlane_b32 s8, v251, 6
	v_readlane_b32 s9, v251, 7
	v_readlane_b32 s10, v251, 8
	v_readlane_b32 s11, v251, 9
	v_readlane_b32 s12, v251, 10
	v_readlane_b32 s13, v251, 11
	v_readlane_b32 s14, v251, 12
	v_readlane_b32 s15, v251, 13
	v_readlane_b32 s16, v251, 14
	v_readlane_b32 s17, v251, 15
	v_addc_co_u32_e32 v13, vcc, 0, v15, vcc
	v_lshlrev_b32_e32 v86, 1, v22
	v_mov_b32_e32 v87, v99
	global_load_dwordx4 v[2:5], v98, s[18:19] offset:16
	global_load_dwordx4 v[26:29], v98, s[18:19]
	v_lshl_add_u64 v[6:7], v[14:15], 0, s[30:31]
	v_lshl_add_u64 v[10:11], v[14:15], 0, s[34:35]
	v_lshl_add_u64 v[16:17], v[14:15], 0, s[76:77]
	v_add_co_u32_e32 v14, vcc, 0x12000, v14
	v_readlane_b32 s4, v251, 26
	v_lshl_add_u64 v[90:91], s[20:21], 0, v[86:87]
	v_or_b32_e32 v54, 1, v95
	v_addc_co_u32_e32 v15, vcc, 0, v15, vcc
	v_readlane_b32 s5, v251, 27
	v_mad_i64_i32 v[22:23], s[2:3], v95, s56, v[90:91]
	v_mad_i64_i32 v[24:25], s[2:3], v54, s56, v[90:91]
	v_or_b32_e32 v55, 2, v95
	v_or_b32_e32 v58, 3, v95
	global_load_dwordx4 v[30:33], v[8:9], off
	s_nop 0
	global_load_dwordx4 v[6:9], v[6:7], off offset:16
	s_nop 0
	global_load_dwordx4 v[34:37], v[12:13], off
	s_nop 0
	global_load_dwordx4 v[10:13], v[10:11], off offset:16
	s_nop 0
	global_load_dwordx4 v[38:41], v[14:15], off
	s_nop 0
	global_load_dwordx4 v[14:17], v[16:17], off offset:16
	s_nop 0
	global_load_dwordx4 v[18:21], v98, s[4:5] offset:16
	global_load_dwordx4 v[42:45], v98, s[4:5]
	global_load_dwordx4 v[66:69], v[22:23], off
	global_load_dwordx4 v[50:53], v[24:25], off
	v_mad_i64_i32 v[22:23], s[2:3], v55, s56, v[90:91]
	v_mad_i64_i32 v[24:25], s[2:3], v58, s56, v[90:91]
	global_load_dwordx4 v[46:49], v[22:23], off
	s_nop 0
	global_load_dwordx4 v[22:25], v[24:25], off
	v_lshl_add_u64 v[56:57], s[36:37], 0, v[98:99]
	v_cmp_lt_i32_e32 vcc, 1, v96
	v_readlane_b32 s6, v251, 28
	v_readlane_b32 s7, v251, 29
	v_readlane_b32 s8, v251, 30
	v_readlane_b32 s9, v251, 31
	v_readlane_b32 s10, v251, 32
	v_readlane_b32 s11, v251, 33
	v_readlane_b32 s12, v251, 34
	v_readlane_b32 s13, v251, 35
	v_readlane_b32 s14, v251, 36
	v_readlane_b32 s15, v251, 37
	v_readlane_b32 s16, v251, 38
	v_readlane_b32 s17, v251, 39
	v_readlane_b32 s18, v251, 40
	v_readlane_b32 s19, v251, 41
	v_cmp_ne_u32_e32 vcc, 1, v96
	s_cbranch_vccnz .Lp7_slow_2
	v_add_u32_e32 v59, -3, v95
	v_mad_i64_i32 v[60:61], s[68:69], v59, s56, v[90:91]
	global_load_dwordx4 v[200:203], v[60:61], off
	v_mad_i64_i32 v[92:93], s[2:3], v95, s56, 0
	v_mad_i64_i32 v[88:89], s[2:3], v54, s56, 0
	v_mad_i64_i32 v[84:85], s[2:3], v55, s56, 0
	v_mad_i64_i32 v[82:83], s[2:3], v58, s56, 0
	v_add_u32_e32 v54, -2, v95
	v_mad_i64_i32 v[54:55], s[68:69], v54, s56, v[90:91]
	global_load_dwordx4 v[204:207], v[54:55], off
	v_add_u32_e32 v54, -1, v95
	v_mad_i64_i32 v[54:55], s[68:69], v54, s56, v[90:91]
	global_load_dwordx4 v[208:211], v[54:55], off
	s_waitcnt vmcnt(0)
	v_lshlrev_b32_e32 v78, 16, v200
	v_and_b32_e32 v79, 0xffff0000, v200
	v_lshlrev_b32_e32 v80, 16, v201
	v_and_b32_e32 v81, 0xffff0000, v201
	v_lshlrev_b32_e32 v70, 16, v202
	v_and_b32_e32 v71, 0xffff0000, v202
	v_lshlrev_b32_e32 v72, 16, v203
	v_and_b32_e32 v73, 0xffff0000, v203
	v_lshlrev_b32_e32 v74, 16, v204
	v_and_b32_e32 v75, 0xffff0000, v204
	v_lshlrev_b32_e32 v76, 16, v205
	v_and_b32_e32 v77, 0xffff0000, v205
	v_lshlrev_b32_e32 v58, 16, v206
	v_and_b32_e32 v59, 0xffff0000, v206
	v_lshlrev_b32_e32 v60, 16, v207
	v_and_b32_e32 v61, 0xffff0000, v207
	v_lshlrev_b32_e32 v62, 16, v208
	v_and_b32_e32 v63, 0xffff0000, v208
	v_lshlrev_b32_e32 v64, 16, v209
	v_and_b32_e32 v65, 0xffff0000, v209
	v_lshlrev_b32_e32 v54, 16, v210
	v_and_b32_e32 v55, 0xffff0000, v210
	v_lshlrev_b32_e32 v56, 16, v211
	v_and_b32_e32 v57, 0xffff0000, v211
	s_branch .Lp7_join_2

; __device__ __forceinline__ float silu_f(float v) { return v * __builtin_amdgcn_rcpf(1.0f + __builtin_amdgcn_exp2f(-1.44269504f * v)); }
; __device__ __forceinline__ unsigned pk2(float lo, float hi) { const cvt_f2 v = {lo, hi}; const cvt_b2 r = __builtin_convertvector(v, cvt_b2); return __builtin_bit_cast(unsigned, r); }
; __device__ __forceinline__ float silu_f(float v) { return v * __builtin_amdgcn_rcpf(1.0f + __builtin_amdgcn_exp2f(-1.44269504f * v)); }
;     ...
;     for (int j = 0; j < NT; ++j) { const v4u r = rr[j];
;         const float cur[8] = {bflo(r.x), bfhi(r.x), bflo(r.y), bfhi(r.y), bflo(r.z), bfhi(r.z), bflo(r.w), bfhi(r.w)}; float o[8];
; #pragma unroll
;         for (int e = 0; e < 8; ++e) { const float a = bias[e] + w[0][e] * h[0][e] + w[1][e] * h[1][e] + w[2][e] * h[2][e] + w[3][e] * cur[e]; o[e] = silu_f(a); h[0][e] = h[1][e]; h[1][e] = h[2][e]; h[2][e] = cur[e]; }
;         v4u pk; pk.x = pk2(o[0], o[1]); pk.y = pk2(o[2], o[3]); pk.z = pk2(o[4], o[5]); pk.w = pk2(o[6], o[7]);
;         __builtin_nontemporal_store(pk, (v4u*)(XC + (size_t)(row0 + j) * B_CD + ch));
.Lp7_join_2:
	s_waitcnt vmcnt(0)
	v_pk_fma_f32 v[78:79], v[26:27], v[78:79], v[42:43]
	v_lshlrev_b32_e32 v90, 16, v66
	v_pk_fma_f32 v[78:79], v[30:31], v[74:75], v[78:79]
	v_and_b32_e32 v91, 0xffff0000, v66
	v_pk_fma_f32 v[78:79], v[34:35], v[62:63], v[78:79]
	v_pk_fma_f32 v[70:71], v[2:3], v[70:71], v[18:19]
	v_pk_fma_f32 v[78:79], v[38:39], v[90:91], v[78:79]
	v_pk_fma_f32 v[70:71], v[6:7], v[58:59], v[70:71]
	v_mul_f32_e32 v66, 0xbfb8aa3b, v78
	v_exp_f32_e32 v66, v66
	v_pk_fma_f32 v[70:71], v[10:11], v[54:55], v[70:71]
	v_mov_b32_e32 v87, v99
	v_lshl_add_u64 v[86:87], s[22:23], 0, v[86:87]
	v_add_f32_e32 v66, 1.0, v66
	v_rcp_f32_e32 v96, v66
	v_mul_f32_e32 v66, 0xbfb8aa3b, v79
	v_exp_f32_e32 v66, v66
	s_nop 0
	v_add_f32_e32 v66, 1.0, v66
	v_rcp_f32_e32 v97, v66
	v_lshlrev_b32_e32 v66, 16, v67
	v_and_b32_e32 v67, 0xffff0000, v67
	v_pk_mul_f32 v[96:97], v[78:79], v[96:97]
	v_pk_fma_f32 v[78:79], v[28:29], v[80:81], v[44:45]
	s_nop 0
	v_pk_fma_f32 v[78:79], v[32:33], v[76:77], v[78:79]
	s_nop 0
	v_pk_fma_f32 v[78:79], v[36:37], v[64:65], v[78:79]
	s_nop 0
	v_pk_fma_f32 v[78:79], v[40:41], v[66:67], v[78:79]
	s_nop 0
	v_mul_f32_e32 v80, 0xbfb8aa3b, v78
	v_mul_f32_e32 v81, 0xbfb8aa3b, v79
	v_exp_f32_e32 v80, v80
	v_exp_f32_e32 v81, v81
	v_add_f32_e32 v80, 1.0, v80
	v_add_f32_e32 v81, 1.0, v81
	v_rcp_f32_e32 v80, v80
	v_rcp_f32_e32 v81, v81
	s_nop 0
	v_pk_mul_f32 v[80:81], v[78:79], v[80:81]
	v_lshlrev_b32_e32 v78, 16, v68
	v_and_b32_e32 v79, 0xffff0000, v68
	v_pk_fma_f32 v[70:71], v[14:15], v[78:79], v[70:71]
	s_nop 0
	v_mul_f32_e32 v68, 0xbfb8aa3b, v70
	v_exp_f32_e32 v68, v68
	s_nop 0
	v_add_f32_e32 v68, 1.0, v68
	v_rcp_f32_e32 v104, v68
	v_mul_f32_e32 v68, 0xbfb8aa3b, v71
	v_exp_f32_e32 v68, v68
	s_nop 0
	v_add_f32_e32 v68, 1.0, v68
	v_rcp_f32_e32 v105, v68
	v_lshlrev_b32_e32 v68, 16, v69
	v_and_b32_e32 v69, 0xffff0000, v69
	v_pk_mul_f32 v[104:105], v[70:71], v[104:105]
	v_pk_fma_f32 v[70:71], v[4:5], v[72:73], v[20:21]
	s_nop 0
	v_pk_fma_f32 v[70:71], v[8:9], v[60:61], v[70:71]
	s_nop 0
	v_pk_fma_f32 v[70:71], v[12:13], v[56:57], v[70:71]
	s_nop 0
	v_pk_fma_f32 v[70:71], v[16:17], v[68:69], v[70:71]
	s_nop 0
	v_mul_f32_e32 v72, 0xbfb8aa3b, v70
	v_mul_f32_e32 v73, 0xbfb8aa3b, v71
	v_exp_f32_e32 v72, v72
	v_exp_f32_e32 v73, v73
	v_add_f32_e32 v72, 1.0, v72
	v_add_f32_e32 v73, 1.0, v73
	v_rcp_f32_e32 v72, v72
	v_rcp_f32_e32 v73, v73
	s_nop 0
	v_pk_mul_f32 v[106:107], v[70:71], v[72:73]
	v_cvt_pk_bf16_f32 v70, v96, v97
	v_cvt_pk_bf16_f32 v71, v80, v81
	v_cvt_pk_bf16_f32 v72, v104, v105
	v_cvt_pk_bf16_f32 v73, v106, v107
	v_lshl_add_u64 v[80:81], v[86:87], 0, v[92:93]
	global_store_dwordx4 v[80:81], v[70:73], off nt
	v_lshlrev_b32_e32 v80, 16, v50
	v_and_b32_e32 v81, 0xffff0000, v50
	v_pk_fma_f32 v[70:71], v[26:27], v[74:75], v[42:43]
	s_nop 0
	v_pk_fma_f32 v[70:71], v[30:31], v[62:63], v[70:71]
	s_nop 0
	v_pk_fma_f32 v[70:71], v[34:35], v[90:91], v[70:71]
	s_nop 0
	v_pk_fma_f32 v[70:71], v[38:39], v[80:81], v[70:71]
	s_nop 0
	v_mul_f32_e32 v50, 0xbfb8aa3b, v70
	v_exp_f32_e32 v50, v50
	s_nop 0
	v_add_f32_e32 v50, 1.0, v50
	v_rcp_f32_e32 v72, v50
	v_mul_f32_e32 v50, 0xbfb8aa3b, v71
	v_exp_f32_e32 v50, v50
	s_nop 0
	v_add_f32_e32 v50, 1.0, v50
	v_rcp_f32_e32 v73, v50
	s_nop 0
	v_pk_mul_f32 v[74:75], v[70:71], v[72:73]
	v_lshlrev_b32_e32 v72, 16, v51
	v_and_b32_e32 v73, 0xffff0000, v51
	v_pk_fma_f32 v[50:51], v[28:29], v[76:77], v[44:45]
	s_nop 0
	v_pk_fma_f32 v[50:51], v[32:33], v[64:65], v[50:51]
	s_nop 0
	v_pk_fma_f32 v[50:51], v[36:37], v[66:67], v[50:51]
	s_nop 0
	v_pk_fma_f32 v[50:51], v[40:41], v[72:73], v[50:51]
	s_nop 0
	v_mul_f32_e32 v70, 0xbfb8aa3b, v50
	v_mul_f32_e32 v71, 0xbfb8aa3b, v51
	v_exp_f32_e32 v70, v70
	v_exp_f32_e32 v71, v71
	v_add_f32_e32 v70, 1.0, v70
	v_add_f32_e32 v71, 1.0, v71
	v_rcp_f32_e32 v70, v70
	v_rcp_f32_e32 v71, v71
	s_nop 0
	v_pk_mul_f32 v[76:77], v[50:51], v[70:71]
	v_pk_fma_f32 v[50:51], v[2:3], v[58:59], v[18:19]
	v_lshlrev_b32_e32 v70, 16, v52
	v_pk_fma_f32 v[50:51], v[6:7], v[54:55], v[50:51]
	v_and_b32_e32 v71, 0xffff0000, v52
	v_pk_fma_f32 v[50:51], v[10:11], v[78:79], v[50:51]
	s_nop 0
	v_pk_fma_f32 v[50:51], v[14:15], v[70:71], v[50:51]
	s_nop 0
	v_mul_f32_e32 v52, 0xbfb8aa3b, v50
	v_exp_f32_e32 v52, v52
	s_nop 0
	v_add_f32_e32 v52, 1.0, v52
	v_rcp_f32_e32 v58, v52
	v_mul_f32_e32 v52, 0xbfb8aa3b, v51
	v_exp_f32_e32 v52, v52
	s_nop 0
	v_add_f32_e32 v52, 1.0, v52
	v_rcp_f32_e32 v59, v52
	s_nop 0
	v_pk_mul_f32 v[92:93], v[50:51], v[58:59]
	v_lshlrev_b32_e32 v50, 16, v53
	v_and_b32_e32 v51, 0xffff0000, v53
	v_pk_fma_f32 v[52:53], v[4:5], v[60:61], v[20:21]
	v_cvt_pk_bf16_f32 v60, v92, v93
	v_pk_fma_f32 v[52:53], v[8:9], v[56:57], v[52:53]
	s_nop 0
	v_pk_fma_f32 v[52:53], v[12:13], v[68:69], v[52:53]
	s_nop 0
	v_pk_fma_f32 v[52:53], v[16:17], v[50:51], v[52:53]
	s_nop 0
	v_mul_f32_e32 v58, 0xbfb8aa3b, v52
	v_mul_f32_e32 v59, 0xbfb8aa3b, v53
	v_exp_f32_e32 v58, v58
	v_exp_f32_e32 v59, v59
	v_add_f32_e32 v58, 1.0, v58
	v_add_f32_e32 v59, 1.0, v59
	v_rcp_f32_e32 v58, v58
	v_rcp_f32_e32 v59, v59
	s_nop 0
	v_pk_mul_f32 v[52:53], v[52:53], v[58:59]
; __device__ __forceinline__ float silu_f(float v) { return v * __builtin_amdgcn_rcpf(1.0f + __builtin_amdgcn_exp2f(-1.44269504f * v)); }
; __device__ __forceinline__ unsigned pk2(float lo, float hi) { const cvt_f2 v = {lo, hi}; const cvt_b2 r = __builtin_convertvector(v, cvt_b2); return __builtin_bit_cast(unsigned, r); }
; __device__ __forceinline__ float silu_f(float v) { return v * __builtin_amdgcn_rcpf(1.0f + __builtin_amdgcn_exp2f(-1.44269504f * v)); }
;     ...
;     for (int j = 0; j < NT; ++j) { const v4u r = rr[j];
;         const float cur[8] = {bflo(r.x), bfhi(r.x), bflo(r.y), bfhi(r.y), bflo(r.z), bfhi(r.z), bflo(r.w), bfhi(r.w)}; float o[8];
; #pragma unroll
;         for (int e = 0; e < 8; ++e) { const float a = bias[e] + w[0][e] * h[0][e] + w[1][e] * h[1][e] + w[2][e] * h[2][e] + w[3][e] * cur[e]; o[e] = silu_f(a); h[0][e] = h[1][e]; h[1][e] = h[2][e]; h[2][e] = cur[e]; }
;         v4u pk; pk.x = pk2(o[0], o[1]); pk.y = pk2(o[2], o[3]); pk.z = pk2(o[4], o[5]); pk.w = pk2(o[6], o[7]);
;         __builtin_nontemporal_store(pk, (v4u*)(XC + (size_t)(row0 + j) * B_CD + ch));
	v_cvt_pk_bf16_f32 v58, v74, v75
	v_cvt_pk_bf16_f32 v59, v76, v77
	v_cvt_pk_bf16_f32 v61, v52, v53
	v_lshl_add_u64 v[52:53], v[86:87], 0, v[88:89]
	global_store_dwordx4 v[52:53], v[58:61], off nt
	v_lshlrev_b32_e32 v52, 16, v46
	v_and_b32_e32 v53, 0xffff0000, v46
	v_pk_fma_f32 v[58:59], v[26:27], v[62:63], v[42:43]
	v_lshlrev_b32_e32 v74, 16, v49
	v_pk_fma_f32 v[58:59], v[30:31], v[90:91], v[58:59]
	v_and_b32_e32 v75, 0xffff0000, v49
	v_pk_fma_f32 v[58:59], v[34:35], v[80:81], v[58:59]
	v_pk_fma_f32 v[26:27], v[26:27], v[90:91], v[42:43]
	v_pk_fma_f32 v[58:59], v[38:39], v[52:53], v[58:59]
	v_pk_fma_f32 v[26:27], v[30:31], v[80:81], v[26:27]
	v_mul_f32_e32 v46, 0xbfb8aa3b, v58
	v_exp_f32_e32 v46, v46
	v_pk_fma_f32 v[26:27], v[34:35], v[52:53], v[26:27]
	v_add_f32_e32 v46, 1.0, v46
	v_rcp_f32_e32 v60, v46
	v_mul_f32_e32 v46, 0xbfb8aa3b, v59
	v_exp_f32_e32 v46, v46
	s_nop 0
	v_add_f32_e32 v46, 1.0, v46
	v_rcp_f32_e32 v61, v46
	s_nop 0
	v_pk_mul_f32 v[58:59], v[58:59], v[60:61]
	v_lshlrev_b32_e32 v60, 16, v47
	v_and_b32_e32 v61, 0xffff0000, v47
	v_pk_fma_f32 v[46:47], v[28:29], v[64:65], v[44:45]
	v_lshlrev_b32_e32 v64, 16, v48
	v_pk_fma_f32 v[46:47], v[32:33], v[66:67], v[46:47]
	v_and_b32_e32 v65, 0xffff0000, v48
	v_pk_fma_f32 v[46:47], v[36:37], v[72:73], v[46:47]
	v_pk_fma_f32 v[28:29], v[28:29], v[66:67], v[44:45]
	v_pk_fma_f32 v[46:47], v[40:41], v[60:61], v[46:47]
	v_pk_fma_f32 v[28:29], v[32:33], v[72:73], v[28:29]
	v_mul_f32_e32 v62, 0xbfb8aa3b, v46
	v_mul_f32_e32 v63, 0xbfb8aa3b, v47
	v_exp_f32_e32 v62, v62
	v_exp_f32_e32 v63, v63
	v_pk_fma_f32 v[28:29], v[36:37], v[60:61], v[28:29]
	v_add_f32_e32 v62, 1.0, v62
	v_add_f32_e32 v63, 1.0, v63
	v_rcp_f32_e32 v62, v62
	v_rcp_f32_e32 v63, v63
	s_nop 0
	v_pk_mul_f32 v[62:63], v[46:47], v[62:63]
	v_pk_fma_f32 v[46:47], v[2:3], v[54:55], v[18:19]
	v_pk_fma_f32 v[2:3], v[2:3], v[78:79], v[18:19]
	v_pk_fma_f32 v[46:47], v[6:7], v[78:79], v[46:47]
	v_pk_fma_f32 v[2:3], v[6:7], v[70:71], v[2:3]
	v_pk_fma_f32 v[46:47], v[10:11], v[70:71], v[46:47]
	v_pk_fma_f32 v[2:3], v[10:11], v[64:65], v[2:3]
	v_pk_fma_f32 v[46:47], v[14:15], v[64:65], v[46:47]
	s_nop 0
	v_mul_f32_e32 v48, 0xbfb8aa3b, v46
	v_exp_f32_e32 v48, v48
	s_nop 0
	v_add_f32_e32 v48, 1.0, v48
	v_rcp_f32_e32 v54, v48
	v_mul_f32_e32 v48, 0xbfb8aa3b, v47
	v_exp_f32_e32 v48, v48
	s_nop 0
	v_add_f32_e32 v48, 1.0, v48
	v_rcp_f32_e32 v55, v48
	s_nop 0
	v_pk_mul_f32 v[54:55], v[46:47], v[54:55]
	v_pk_fma_f32 v[46:47], v[4:5], v[56:57], v[20:21]
	v_pk_fma_f32 v[4:5], v[4:5], v[68:69], v[20:21]
	v_pk_fma_f32 v[46:47], v[8:9], v[68:69], v[46:47]
	v_pk_fma_f32 v[4:5], v[8:9], v[50:51], v[4:5]
	v_pk_fma_f32 v[46:47], v[12:13], v[50:51], v[46:47]
	v_pk_fma_f32 v[4:5], v[12:13], v[74:75], v[4:5]
	v_pk_fma_f32 v[46:47], v[16:17], v[74:75], v[46:47]
	s_nop 0
	v_mul_f32_e32 v48, 0xbfb8aa3b, v46
	v_mul_f32_e32 v49, 0xbfb8aa3b, v47
	v_exp_f32_e32 v48, v48
	v_exp_f32_e32 v49, v49
	v_add_f32_e32 v48, 1.0, v48
	v_add_f32_e32 v49, 1.0, v49
	v_rcp_f32_e32 v48, v48
	v_rcp_f32_e32 v49, v49
	s_nop 0
	v_pk_mul_f32 v[56:57], v[46:47], v[48:49]
	v_cvt_pk_bf16_f32 v46, v58, v59
	v_cvt_pk_bf16_f32 v47, v62, v63
	v_cvt_pk_bf16_f32 v48, v54, v55
	v_cvt_pk_bf16_f32 v49, v56, v57
	v_lshl_add_u64 v[54:55], v[86:87], 0, v[84:85]
	global_store_dwordx4 v[54:55], v[46:49], off nt
	s_nop 1
	v_lshlrev_b32_e32 v46, 16, v22
	v_and_b32_e32 v47, 0xffff0000, v22
	v_pk_fma_f32 v[26:27], v[38:39], v[46:47], v[26:27]
	s_nop 0
	v_mul_f32_e32 v22, 0xbfb8aa3b, v26
	v_exp_f32_e32 v22, v22
	s_nop 0
	v_add_f32_e32 v22, 1.0, v22
	v_rcp_f32_e32 v30, v22
	v_mul_f32_e32 v22, 0xbfb8aa3b, v27
	v_exp_f32_e32 v22, v22
	s_nop 0
	v_add_f32_e32 v22, 1.0, v22
	v_rcp_f32_e32 v31, v22
	v_lshlrev_b32_e32 v22, 16, v23
	v_and_b32_e32 v23, 0xffff0000, v23
	v_pk_fma_f32 v[22:23], v[40:41], v[22:23], v[28:29]
	v_pk_mul_f32 v[26:27], v[26:27], v[30:31]
	v_mul_f32_e32 v28, 0xbfb8aa3b, v22
	v_mul_f32_e32 v29, 0xbfb8aa3b, v23
	v_exp_f32_e32 v28, v28
	v_exp_f32_e32 v29, v29
	v_add_f32_e32 v28, 1.0, v28
	v_add_f32_e32 v29, 1.0, v29
	v_rcp_f32_e32 v28, v28
	v_rcp_f32_e32 v29, v29
	s_nop 0
	v_pk_mul_f32 v[22:23], v[22:23], v[28:29]
	v_lshlrev_b32_e32 v28, 16, v24
	v_and_b32_e32 v29, 0xffff0000, v24
	v_pk_fma_f32 v[2:3], v[14:15], v[28:29], v[2:3]
	s_nop 0
	v_mul_f32_e32 v6, 0xbfb8aa3b, v2
	v_mul_f32_e32 v7, 0xbfb8aa3b, v3
	v_exp_f32_e32 v6, v6
	v_exp_f32_e32 v7, v7
	v_add_f32_e32 v6, 1.0, v6
	v_add_f32_e32 v7, 1.0, v7
	v_rcp_f32_e32 v6, v6
	v_rcp_f32_e32 v7, v7
	s_nop 0
	v_pk_mul_f32 v[6:7], v[2:3], v[6:7]
	v_lshlrev_b32_e32 v2, 16, v25
	v_and_b32_e32 v3, 0xffff0000, v25
	v_pk_fma_f32 v[2:3], v[16:17], v[2:3], v[4:5]
	s_nop 0
	v_mul_f32_e32 v4, 0xbfb8aa3b, v2
	v_mul_f32_e32 v5, 0xbfb8aa3b, v3
	v_exp_f32_e32 v4, v4
	v_exp_f32_e32 v5, v5
	v_add_f32_e32 v4, 1.0, v4
	v_add_f32_e32 v5, 1.0, v5
	v_rcp_f32_e32 v4, v4
	v_rcp_f32_e32 v5, v5
	s_nop 0
	v_pk_mul_f32 v[8:9], v[2:3], v[4:5]
	v_cvt_pk_bf16_f32 v2, v26, v27
	v_cvt_pk_bf16_f32 v3, v22, v23
	v_cvt_pk_bf16_f32 v4, v6, v7
	v_cvt_pk_bf16_f32 v5, v8, v9
	v_lshl_add_u64 v[6:7], v[86:87], 0, v[82:83]
	global_store_dwordx4 v[6:7], v[2:5], off nt
